# conservative final candidate: v59 without the early B-fragment LDS reads (they ran ahead of the other wave half's DMA wait), without the barrier and deal changes; keeps prio3, saddr DMA, merged waits,
# speedup vs baseline: 1.0004x; 1.0004x over previous
; #define PG8_STAGE(bufoff, gbase, voff) do { _Pragma("unroll") for (int _i = 0; _i < 2; ++_i) \
;         __builtin_amdgcn_global_load_lds((const unsigned*)((const char*)(gbase) + (voff)[_i]), (PG8_LAS unsigned*)(lds + (bufoff) + ldsw + _i * 8192), 16, 0, 0); } while (0)
; #define PG8_LDA(dst, b, h) do { _Pragma("unroll") for (int m = 0; m < 4; ++m) _Pragma("unroll") for (int k = 0; k < 2; ++k) dst[m][k] = *(const PG8_LAS bf16x8*)(lds + PG8_SA(b, h) + aoff + m * 2048 + k * 1024); } while (0)
; #define PG8_LDB(dst, b, h) do { _Pragma("unroll") for (int n = 0; n < 2; ++n) _Pragma("unroll") for (int k = 0; k < 2; ++k) dst[n][k] = *(const PG8_LAS bf16x8*)(lds + PG8_SB(b, h) + boff + n * 2048 + k * 1024); } while (0)
; #define PG8_MMA(ai, bj, At, Bt) do { __builtin_amdgcn_s_setprio(1); _Pragma("unroll") for (int m = 0; m < 4; ++m) _Pragma("unroll") for (int n = 0; n < 2; ++n) _Pragma("unroll") for (int k = 0; k < 2; ++k) \
;         acc[ai][bj][m][n] = __builtin_amdgcn_mfma_f32_16x16x32_bf16(Bt[n][k], At[m][k], acc[ai][bj][m][n], 0, 0, 0); __builtin_amdgcn_s_setprio(0); } while (0)
; #define PG8_WAIT_V(n) asm volatile("s_waitcnt vmcnt(" #n ")" ::: "memory")
; #define PG8_WAIT_L(n) asm volatile("s_waitcnt lgkmcnt(" #n ")" ::: "memory")
; #define PG8_BAR __builtin_amdgcn_s_barrier()
; #define PG8_SCHED __builtin_amdgcn_sched_barrier(0)
; template <class Epi, class Sched, bool ALIGN_EPI = false, bool SP2 = false>
; __device__ __forceinline__ void gemm_phase(PG8_LAS unsigned char* lds, const Gemm g, const Sched& S, const Epi& E) {
;     ...
;             PG8_LDB(B0, 0, 0); PG8_LDB(B1, 0, 1); PG8_SCHED; PG8_LDA(At, 0, 0); PG8_STAGE(PG8_SA(1, 1), a1 + hstep, voffA);
;             PG8_WAIT_V(8); PG8_WAIT_L(0); PG8_BAR; PG8_MMA(0, 0, At, B0); PG8_MMA(0, 1, At, B1); PG8_BAR; PG8_SCHED;
;             PG8_LDA(At, 0, 1); PG8_STAGE(PG8_SB(0, 0), b2, voffB); PG8_STAGE(PG8_SB(0, 1), b2 + hstep, voffB); PG8_STAGE(PG8_SA(0, 0), a2, voffA);
;             PG8_WAIT_V(8); PG8_WAIT_L(0); PG8_BAR; PG8_MMA(1, 0, At, B0); PG8_MMA(1, 1, At, B1); PG8_BAR; PG8_SCHED;
.LBB0_301:
	s_add_u32 s38, s36, 0xfff80080
	s_addc_u32 s39, s37, -1
	s_add_i32 s61, 0, 0x10000
	s_cmp_eq_u32 s60, 28
	s_cselect_b32 s41, s11, s39
	s_cselect_b32 s40, s13, s38
	s_cselect_b32 s39, s56, s59
	s_cselect_b32 s38, s57, s58
	s_add_i32 s64, 0, 0x14000
	ds_read_b128 v[142:145], v249
	ds_read_b128 v[146:149], v249 offset:1024
	ds_read_b128 v[154:157], v249 offset:2048
	ds_read_b128 v[158:161], v249 offset:3072
	ds_read_b128 v[174:177], v249 offset:16384
	ds_read_b128 v[178:181], v249 offset:17408
	ds_read_b128 v[204:207], v249 offset:18432
	ds_read_b128 v[208:211], v249 offset:19456
	s_add_i32 m0, s47, 0xc000
	ds_read_b128 v[212:215], v153
	ds_read_b128 v[216:219], v153 offset:1024
	ds_read_b128 v[220:223], v153 offset:2048
	ds_read_b128 v[224:227], v153 offset:3072
	ds_read_b128 v[228:231], v153 offset:4096
	ds_read_b128 v[232:235], v153 offset:5120
	ds_read_b128 v[236:239], v153 offset:6144
	ds_read_b128 v[240:243], v153 offset:7168
	global_load_lds_dwordx4 v138, s[36:37]
	s_add_i32 m0, s47, 0xe000
	s_nop 0
	global_load_lds_dwordx4 v140, s[36:37]
	s_waitcnt vmcnt(8) lgkmcnt(0)
	s_setprio 0
	s_barrier
	v_mfma_f32_16x16x32_bf16 v[128:131], v[142:145], v[212:215], v[128:131]
	v_mfma_f32_16x16x32_bf16 v[120:123], v[154:157], v[212:215], v[120:123]
	v_mfma_f32_16x16x32_bf16 v[112:115], v[142:145], v[220:223], v[112:115]
	v_mfma_f32_16x16x32_bf16 v[104:107], v[154:157], v[220:223], v[104:107]
	v_mfma_f32_16x16x32_bf16 v[96:99], v[142:145], v[228:231], v[96:99]
	v_mfma_f32_16x16x32_bf16 v[88:91], v[154:157], v[228:231], v[88:91]
	v_mfma_f32_16x16x32_bf16 v[80:83], v[142:145], v[236:239], v[80:83]
	v_mfma_f32_16x16x32_bf16 v[72:75], v[154:157], v[236:239], v[72:75]
	v_mfma_f32_16x16x32_bf16 v[128:131], v[146:149], v[216:219], v[128:131]
	v_mfma_f32_16x16x32_bf16 v[120:123], v[158:161], v[216:219], v[120:123]
	v_mfma_f32_16x16x32_bf16 v[112:115], v[146:149], v[224:227], v[112:115]
	v_mfma_f32_16x16x32_bf16 v[104:107], v[158:161], v[224:227], v[104:107]
	v_mfma_f32_16x16x32_bf16 v[96:99], v[146:149], v[232:235], v[96:99]
	v_mfma_f32_16x16x32_bf16 v[88:91], v[158:161], v[232:235], v[88:91]
	v_mfma_f32_16x16x32_bf16 v[80:83], v[146:149], v[240:243], v[80:83]
	v_mfma_f32_16x16x32_bf16 v[72:75], v[158:161], v[240:243], v[72:75]
	v_mfma_f32_16x16x32_bf16 v[124:127], v[174:177], v[212:215], v[124:127]
	v_mfma_f32_16x16x32_bf16 v[116:119], v[204:207], v[212:215], v[116:119]
	v_mfma_f32_16x16x32_bf16 v[108:111], v[174:177], v[220:223], v[108:111]
	v_mfma_f32_16x16x32_bf16 v[100:103], v[204:207], v[220:223], v[100:103]
	v_mfma_f32_16x16x32_bf16 v[92:95], v[174:177], v[228:231], v[92:95]
	v_mfma_f32_16x16x32_bf16 v[84:87], v[204:207], v[228:231], v[84:87]
	v_mfma_f32_16x16x32_bf16 v[76:79], v[174:177], v[236:239], v[76:79]
	v_mfma_f32_16x16x32_bf16 v[68:71], v[204:207], v[236:239], v[68:71]
	v_mfma_f32_16x16x32_bf16 v[124:127], v[178:181], v[216:219], v[124:127]
	v_mfma_f32_16x16x32_bf16 v[116:119], v[208:211], v[216:219], v[116:119]
	v_mfma_f32_16x16x32_bf16 v[108:111], v[178:181], v[224:227], v[108:111]
	v_mfma_f32_16x16x32_bf16 v[100:103], v[208:211], v[224:227], v[100:103]
	v_mfma_f32_16x16x32_bf16 v[92:95], v[178:181], v[232:235], v[92:95]
	v_mfma_f32_16x16x32_bf16 v[84:87], v[208:211], v[232:235], v[84:87]
	v_mfma_f32_16x16x32_bf16 v[76:79], v[178:181], v[240:243], v[76:79]
	v_mfma_f32_16x16x32_bf16 v[68:71], v[208:211], v[240:243], v[68:71]
	s_setprio 3
	s_barrier
	s_add_i32 s61, s61, s42
	s_mov_b32 m0, s61
	ds_read_b128 v[212:215], v153 offset:16384
	ds_read_b128 v[216:219], v153 offset:17408
	ds_read_b128 v[220:223], v153 offset:18432
	ds_read_b128 v[224:227], v153 offset:19456
	ds_read_b128 v[228:231], v153 offset:20480
	ds_read_b128 v[232:235], v153 offset:21504
	ds_read_b128 v[236:239], v153 offset:22528
	ds_read_b128 v[240:243], v153 offset:23552
	global_load_lds_dwordx4 v2, s[38:39]
	s_add_i32 m0, s61, 0x2000
	s_add_u32 s62, s38, 0x80000
	s_addc_u32 s63, s39, 0
	s_add_i32 s61, s64, s42
	global_load_lds_dwordx4 v132, s[38:39]
	s_mov_b32 m0, s61
	s_nop 0
	global_load_lds_dwordx4 v2, s[62:63]
	s_add_i32 m0, s61, 0x2000
	s_nop 0
	global_load_lds_dwordx4 v132, s[62:63]
	s_mov_b32 m0, s47
	s_nop 0
	global_load_lds_dwordx4 v136, s[40:41]
	s_mov_b32 m0, s48
	s_nop 0
	global_load_lds_dwordx4 v134, s[40:41]
	s_waitcnt vmcnt(8) lgkmcnt(0)
	s_setprio 0
	s_barrier
	v_mfma_f32_16x16x32_bf16 v[64:67], v[142:145], v[212:215], v[64:67]
	v_mfma_f32_16x16x32_bf16 v[56:59], v[154:157], v[212:215], v[56:59]
	v_mfma_f32_16x16x32_bf16 v[48:51], v[142:145], v[220:223], v[48:51]
	v_mfma_f32_16x16x32_bf16 v[40:43], v[154:157], v[220:223], v[40:43]
	v_mfma_f32_16x16x32_bf16 v[32:35], v[142:145], v[228:231], v[32:35]
	v_mfma_f32_16x16x32_bf16 v[24:27], v[154:157], v[228:231], v[24:27]
	v_mfma_f32_16x16x32_bf16 v[16:19], v[142:145], v[236:239], v[16:19]
	v_mfma_f32_16x16x32_bf16 v[8:11], v[154:157], v[236:239], v[8:11]
	v_mfma_f32_16x16x32_bf16 v[64:67], v[146:149], v[216:219], v[64:67]
	v_mfma_f32_16x16x32_bf16 v[56:59], v[158:161], v[216:219], v[56:59]
	v_mfma_f32_16x16x32_bf16 v[48:51], v[146:149], v[224:227], v[48:51]
	v_mfma_f32_16x16x32_bf16 v[40:43], v[158:161], v[224:227], v[40:43]
	v_mfma_f32_16x16x32_bf16 v[32:35], v[146:149], v[232:235], v[32:35]
	v_mfma_f32_16x16x32_bf16 v[24:27], v[158:161], v[232:235], v[24:27]
	v_mfma_f32_16x16x32_bf16 v[16:19], v[146:149], v[240:243], v[16:19]
	v_mfma_f32_16x16x32_bf16 v[8:11], v[158:161], v[240:243], v[8:11]
	v_mfma_f32_16x16x32_bf16 v[60:63], v[174:177], v[212:215], v[60:63]
	v_mfma_f32_16x16x32_bf16 v[52:55], v[204:207], v[212:215], v[52:55]
	v_mfma_f32_16x16x32_bf16 v[44:47], v[174:177], v[220:223], v[44:47]
	v_mfma_f32_16x16x32_bf16 v[36:39], v[204:207], v[220:223], v[36:39]
	v_mfma_f32_16x16x32_bf16 v[28:31], v[174:177], v[228:231], v[28:31]
	v_mfma_f32_16x16x32_bf16 v[20:23], v[204:207], v[228:231], v[20:23]
	v_mfma_f32_16x16x32_bf16 v[12:15], v[174:177], v[236:239], v[12:15]
	v_mfma_f32_16x16x32_bf16 v[4:7], v[204:207], v[236:239], v[4:7]
	v_mfma_f32_16x16x32_bf16 v[60:63], v[178:181], v[216:219], v[60:63]
	v_mfma_f32_16x16x32_bf16 v[52:55], v[208:211], v[216:219], v[52:55]
	v_mfma_f32_16x16x32_bf16 v[44:47], v[178:181], v[224:227], v[44:47]
	v_mfma_f32_16x16x32_bf16 v[36:39], v[208:211], v[224:227], v[36:39]
	v_mfma_f32_16x16x32_bf16 v[28:31], v[178:181], v[232:235], v[28:31]
	v_mfma_f32_16x16x32_bf16 v[20:23], v[208:211], v[232:235], v[20:23]
	v_mfma_f32_16x16x32_bf16 v[12:15], v[178:181], v[240:243], v[12:15]
	v_mfma_f32_16x16x32_bf16 v[4:7], v[208:211], v[240:243], v[4:7]
	s_setprio 3
	s_barrier
; #define PG8_STAGE(bufoff, gbase, voff) do { _Pragma("unroll") for (int _i = 0; _i < 2; ++_i) \
;         __builtin_amdgcn_global_load_lds((const unsigned*)((const char*)(gbase) + (voff)[_i]), (PG8_LAS unsigned*)(lds + (bufoff) + ldsw + _i * 8192), 16, 0, 0); } while (0)
; #define PG8_LDA(dst, b, h) do { _Pragma("unroll") for (int m = 0; m < 4; ++m) _Pragma("unroll") for (int k = 0; k < 2; ++k) dst[m][k] = *(const PG8_LAS bf16x8*)(lds + PG8_SA(b, h) + aoff + m * 2048 + k * 1024); } while (0)
; #define PG8_LDB(dst, b, h) do { _Pragma("unroll") for (int n = 0; n < 2; ++n) _Pragma("unroll") for (int k = 0; k < 2; ++k) dst[n][k] = *(const PG8_LAS bf16x8*)(lds + PG8_SB(b, h) + boff + n * 2048 + k * 1024); } while (0)
; #define PG8_MMA(ai, bj, At, Bt) do { __builtin_amdgcn_s_setprio(1); _Pragma("unroll") for (int m = 0; m < 4; ++m) _Pragma("unroll") for (int n = 0; n < 2; ++n) _Pragma("unroll") for (int k = 0; k < 2; ++k) \
;         acc[ai][bj][m][n] = __builtin_amdgcn_mfma_f32_16x16x32_bf16(Bt[n][k], At[m][k], acc[ai][bj][m][n], 0, 0, 0); __builtin_amdgcn_s_setprio(0); } while (0)
; #define PG8_WAIT_V(n) asm volatile("s_waitcnt vmcnt(" #n ")" ::: "memory")
; #define PG8_WAIT_L(n) asm volatile("s_waitcnt lgkmcnt(" #n ")" ::: "memory")
; #define PG8_BAR __builtin_amdgcn_s_barrier()
; #define PG8_SCHED __builtin_amdgcn_sched_barrier(0)
; template <class Epi, class Sched, bool ALIGN_EPI = false, bool SP2 = false>
; __device__ __forceinline__ void gemm_phase(PG8_LAS unsigned char* lds, const Gemm g, const Sched& S, const Epi& E) {
;     ...
;             PG8_LDB(B0, 1, 0); PG8_LDB(B1, 1, 1); PG8_SCHED; PG8_LDA(At, 1, 0); PG8_STAGE(PG8_SA(0, 1), a2 + hstep, voffA);
;             PG8_WAIT_V(8); PG8_WAIT_L(0); PG8_BAR; PG8_MMA(0, 0, At, B0); PG8_MMA(0, 1, At, B1); PG8_BAR; PG8_SCHED;
;             PG8_LDA(At, 1, 1); PG8_STAGE(PG8_SB(1, 0), b3, voffB); PG8_STAGE(PG8_SB(1, 1), b3 + hstep, voffB); PG8_STAGE(PG8_SA(1, 0), a3, voffA);
;             PG8_WAIT_V(8); PG8_WAIT_L(0); PG8_BAR; PG8_MMA(1, 0, At, B0); PG8_MMA(1, 1, At, B1); PG8_BAR; PG8_SCHED;
	s_add_i32 s61, 0, 0x18000
	s_add_i32 s62, 0, 0x1c000
	ds_read_b128 v[142:145], v249 offset:32768
	ds_read_b128 v[146:149], v249 offset:33792
	ds_read_b128 v[154:157], v249 offset:34816
	ds_read_b128 v[158:161], v249 offset:35840
	ds_read_b128 v[174:177], v249 offset:49152
	ds_read_b128 v[178:181], v249 offset:50176
	ds_read_b128 v[204:207], v249 offset:51200
	ds_read_b128 v[208:211], v249 offset:52224
	s_add_u32 s100, s40, 0x80
	s_addc_u32 s101, s41, 0
	s_add_u32 s40, s40, 0x80000
	s_addc_u32 s41, s41, 0
	s_mov_b32 m0, s49
	ds_read_b128 v[212:215], v153 offset:32768
	ds_read_b128 v[216:219], v153 offset:33792
	ds_read_b128 v[220:223], v153 offset:34816
	ds_read_b128 v[224:227], v153 offset:35840
	ds_read_b128 v[228:231], v153 offset:36864
	ds_read_b128 v[232:235], v153 offset:37888
	ds_read_b128 v[236:239], v153 offset:38912
	ds_read_b128 v[240:243], v153 offset:39936
	global_load_lds_dwordx4 v136, s[40:41]
	s_mov_b32 m0, s50
	s_nop 0
	global_load_lds_dwordx4 v134, s[40:41]
	s_waitcnt vmcnt(8) lgkmcnt(0)
	s_setprio 0
	s_barrier
	v_mfma_f32_16x16x32_bf16 v[128:131], v[142:145], v[212:215], v[128:131]
	v_mfma_f32_16x16x32_bf16 v[120:123], v[154:157], v[212:215], v[120:123]
	v_mfma_f32_16x16x32_bf16 v[112:115], v[142:145], v[220:223], v[112:115]
	v_mfma_f32_16x16x32_bf16 v[104:107], v[154:157], v[220:223], v[104:107]
	v_mfma_f32_16x16x32_bf16 v[96:99], v[142:145], v[228:231], v[96:99]
	v_mfma_f32_16x16x32_bf16 v[88:91], v[154:157], v[228:231], v[88:91]
	v_mfma_f32_16x16x32_bf16 v[80:83], v[142:145], v[236:239], v[80:83]
	v_mfma_f32_16x16x32_bf16 v[72:75], v[154:157], v[236:239], v[72:75]
	v_mfma_f32_16x16x32_bf16 v[128:131], v[146:149], v[216:219], v[128:131]
	v_mfma_f32_16x16x32_bf16 v[120:123], v[158:161], v[216:219], v[120:123]
	v_mfma_f32_16x16x32_bf16 v[112:115], v[146:149], v[224:227], v[112:115]
	v_mfma_f32_16x16x32_bf16 v[104:107], v[158:161], v[224:227], v[104:107]
	v_mfma_f32_16x16x32_bf16 v[96:99], v[146:149], v[232:235], v[96:99]
	v_mfma_f32_16x16x32_bf16 v[88:91], v[158:161], v[232:235], v[88:91]
	v_mfma_f32_16x16x32_bf16 v[80:83], v[146:149], v[240:243], v[80:83]
	v_mfma_f32_16x16x32_bf16 v[72:75], v[158:161], v[240:243], v[72:75]
	v_mfma_f32_16x16x32_bf16 v[124:127], v[174:177], v[212:215], v[124:127]
	v_mfma_f32_16x16x32_bf16 v[116:119], v[204:207], v[212:215], v[116:119]
	v_mfma_f32_16x16x32_bf16 v[108:111], v[174:177], v[220:223], v[108:111]
	v_mfma_f32_16x16x32_bf16 v[100:103], v[204:207], v[220:223], v[100:103]
	v_mfma_f32_16x16x32_bf16 v[92:95], v[174:177], v[228:231], v[92:95]
	v_mfma_f32_16x16x32_bf16 v[84:87], v[204:207], v[228:231], v[84:87]
	v_mfma_f32_16x16x32_bf16 v[76:79], v[174:177], v[236:239], v[76:79]
	v_mfma_f32_16x16x32_bf16 v[68:71], v[204:207], v[236:239], v[68:71]
	v_mfma_f32_16x16x32_bf16 v[124:127], v[178:181], v[216:219], v[124:127]
	v_mfma_f32_16x16x32_bf16 v[116:119], v[208:211], v[216:219], v[116:119]
	v_mfma_f32_16x16x32_bf16 v[108:111], v[178:181], v[224:227], v[108:111]
	v_mfma_f32_16x16x32_bf16 v[100:103], v[208:211], v[224:227], v[100:103]
	v_mfma_f32_16x16x32_bf16 v[92:95], v[178:181], v[232:235], v[92:95]
	v_mfma_f32_16x16x32_bf16 v[84:87], v[208:211], v[232:235], v[84:87]
	v_mfma_f32_16x16x32_bf16 v[76:79], v[178:181], v[240:243], v[76:79]
	v_mfma_f32_16x16x32_bf16 v[68:71], v[208:211], v[240:243], v[68:71]
	s_setprio 3
	s_barrier
	s_add_i32 s40, s61, s42
	s_add_i32 m0, s40, 0xffffff80
	ds_read_b128 v[212:215], v153 offset:49152
	ds_read_b128 v[216:219], v153 offset:50176
	ds_read_b128 v[220:223], v153 offset:51200
	ds_read_b128 v[224:227], v153 offset:52224
	ds_read_b128 v[228:231], v153 offset:53248
	ds_read_b128 v[232:235], v153 offset:54272
	ds_read_b128 v[236:239], v153 offset:55296
	ds_read_b128 v[240:243], v153 offset:56320
	global_load_lds_dwordx4 v2, s[38:39] offset:128
	s_add_i32 m0, s40, 0x1f80
	s_add_i32 s40, s62, s42
	global_load_lds_dwordx4 v132, s[38:39] offset:128
	s_add_u32 s38, s38, 0x80080
	s_addc_u32 s39, s39, 0
	s_mov_b32 m0, s40
	s_nop 0
	global_load_lds_dwordx4 v2, s[38:39]
	s_add_i32 m0, s40, 0x2000
	s_nop 0
	global_load_lds_dwordx4 v132, s[38:39]
	s_mov_b32 m0, s51
	s_nop 0
	global_load_lds_dwordx4 v136, s[100:101]
	s_mov_b32 m0, s53
	s_nop 0
	global_load_lds_dwordx4 v134, s[100:101]
	s_nop 0
	s_waitcnt vmcnt(8) lgkmcnt(0)
	s_setprio 0
	s_barrier
	v_mfma_f32_16x16x32_bf16 v[64:67], v[142:145], v[212:215], v[64:67]
	v_mfma_f32_16x16x32_bf16 v[56:59], v[154:157], v[212:215], v[56:59]
	v_mfma_f32_16x16x32_bf16 v[48:51], v[142:145], v[220:223], v[48:51]
	v_mfma_f32_16x16x32_bf16 v[40:43], v[154:157], v[220:223], v[40:43]
	v_mfma_f32_16x16x32_bf16 v[32:35], v[142:145], v[228:231], v[32:35]
	v_mfma_f32_16x16x32_bf16 v[24:27], v[154:157], v[228:231], v[24:27]
	v_mfma_f32_16x16x32_bf16 v[16:19], v[142:145], v[236:239], v[16:19]
	v_mfma_f32_16x16x32_bf16 v[8:11], v[154:157], v[236:239], v[8:11]
	v_mfma_f32_16x16x32_bf16 v[64:67], v[146:149], v[216:219], v[64:67]
	v_mfma_f32_16x16x32_bf16 v[56:59], v[158:161], v[216:219], v[56:59]
	v_mfma_f32_16x16x32_bf16 v[48:51], v[146:149], v[224:227], v[48:51]
	v_mfma_f32_16x16x32_bf16 v[40:43], v[158:161], v[224:227], v[40:43]
	v_mfma_f32_16x16x32_bf16 v[32:35], v[146:149], v[232:235], v[32:35]
	v_mfma_f32_16x16x32_bf16 v[24:27], v[158:161], v[232:235], v[24:27]
	v_mfma_f32_16x16x32_bf16 v[16:19], v[146:149], v[240:243], v[16:19]
	v_mfma_f32_16x16x32_bf16 v[8:11], v[158:161], v[240:243], v[8:11]
	v_mfma_f32_16x16x32_bf16 v[60:63], v[174:177], v[212:215], v[60:63]
	v_mfma_f32_16x16x32_bf16 v[52:55], v[204:207], v[212:215], v[52:55]
	v_mfma_f32_16x16x32_bf16 v[44:47], v[174:177], v[220:223], v[44:47]
	v_mfma_f32_16x16x32_bf16 v[36:39], v[204:207], v[220:223], v[36:39]
	v_mfma_f32_16x16x32_bf16 v[28:31], v[174:177], v[228:231], v[28:31]
	v_mfma_f32_16x16x32_bf16 v[20:23], v[204:207], v[228:231], v[20:23]
	v_mfma_f32_16x16x32_bf16 v[12:15], v[174:177], v[236:239], v[12:15]
	v_mfma_f32_16x16x32_bf16 v[4:7], v[204:207], v[236:239], v[4:7]
	v_mfma_f32_16x16x32_bf16 v[60:63], v[178:181], v[216:219], v[60:63]
	v_mfma_f32_16x16x32_bf16 v[52:55], v[208:211], v[216:219], v[52:55]
	v_mfma_f32_16x16x32_bf16 v[44:47], v[178:181], v[224:227], v[44:47]
	v_mfma_f32_16x16x32_bf16 v[36:39], v[208:211], v[224:227], v[36:39]
	v_mfma_f32_16x16x32_bf16 v[28:31], v[178:181], v[232:235], v[28:31]
	v_mfma_f32_16x16x32_bf16 v[20:23], v[208:211], v[232:235], v[20:23]
	v_mfma_f32_16x16x32_bf16 v[12:15], v[178:181], v[240:243], v[12:15]
	v_mfma_f32_16x16x32_bf16 v[4:7], v[208:211], v[240:243], v[4:7]
	s_setprio 3
	s_barrier
	s_add_i32 s60, s60, 2
	s_add_u32 s36, s36, 0x100
	s_addc_u32 s37, s37, 0
	s_add_u32 s58, s58, 0x100
	s_addc_u32 s59, s59, 0
	s_cmp_gt_u32 s60, 29
	s_cbranch_scc0 .LBB0_301
	s_and_b64 vcc, exec, s[8:9]
	s_cbranch_vccz .LBB0_304
	s_barrier

; #define PG8_STAGE(bufoff, gbase, voff) do { _Pragma("unroll") for (int _i = 0; _i < 2; ++_i) \
;         __builtin_amdgcn_global_load_lds((const unsigned*)((const char*)(gbase) + (voff)[_i]), (PG8_LAS unsigned*)(lds + (bufoff) + ldsw + _i * 8192), 16, 0, 0); } while (0)
; #define PG8_LDA(dst, b, h) do { _Pragma("unroll") for (int m = 0; m < 4; ++m) _Pragma("unroll") for (int k = 0; k < 2; ++k) dst[m][k] = *(const PG8_LAS bf16x8*)(lds + PG8_SA(b, h) + aoff + m * 2048 + k * 1024); } while (0)
; #define PG8_LDB(dst, b, h) do { _Pragma("unroll") for (int n = 0; n < 2; ++n) _Pragma("unroll") for (int k = 0; k < 2; ++k) dst[n][k] = *(const PG8_LAS bf16x8*)(lds + PG8_SB(b, h) + boff + n * 2048 + k * 1024); } while (0)
; #define PG8_MMA(ai, bj, At, Bt) do { __builtin_amdgcn_s_setprio(1); _Pragma("unroll") for (int m = 0; m < 4; ++m) _Pragma("unroll") for (int n = 0; n < 2; ++n) _Pragma("unroll") for (int k = 0; k < 2; ++k) \
;         acc[ai][bj][m][n] = __builtin_amdgcn_mfma_f32_16x16x32_bf16(Bt[n][k], At[m][k], acc[ai][bj][m][n], 0, 0, 0); __builtin_amdgcn_s_setprio(0); } while (0)
; #define PG8_WAIT_V(n) asm volatile("s_waitcnt vmcnt(" #n ")" ::: "memory")
; #define PG8_WAIT_L(n) asm volatile("s_waitcnt lgkmcnt(" #n ")" ::: "memory")
; #define PG8_BAR __builtin_amdgcn_s_barrier()
; #define PG8_SCHED __builtin_amdgcn_sched_barrier(0)
; template <class Epi, class Sched, bool ALIGN_EPI = false, bool SP2 = false>
; __device__ __forceinline__ void gemm_phase(PG8_LAS unsigned char* lds, const Gemm g, const Sched& S, const Epi& E) {
;     ...
;             PG8_LDB(B0, 0, 0); PG8_LDB(B1, 0, 1); PG8_SCHED; PG8_LDA(At, 0, 0); PG8_STAGE(PG8_SA(1, 1), a1 + hstep, voffA);
;             PG8_WAIT_V(8); PG8_WAIT_L(0); PG8_BAR; PG8_MMA(0, 0, At, B0); PG8_MMA(0, 1, At, B1); PG8_BAR; PG8_SCHED;
;             PG8_LDA(At, 0, 1); PG8_STAGE(PG8_SB(0, 0), b2, voffB); PG8_STAGE(PG8_SB(0, 1), b2 + hstep, voffB); PG8_STAGE(PG8_SA(0, 0), a2, voffA);
;             PG8_WAIT_V(8); PG8_WAIT_L(0); PG8_BAR; PG8_MMA(1, 0, At, B0); PG8_MMA(1, 1, At, B1); PG8_BAR; PG8_SCHED;
.LBB0_575:
	s_add_u32 s36, s34, 0x100
	s_addc_u32 s37, s35, 0
	s_add_i32 s64, 0, 0x10000
	s_cmpk_eq_i32 s63, 0x52
	s_cselect_b32 s41, s5, s37
	s_cselect_b32 s40, s4, s36
	s_cselect_b32 s39, s31, s62
	s_cselect_b32 s38, s30, s61
	s_add_i32 s65, 0, 0x14000
	ds_read_b128 v[142:145], v247
	ds_read_b128 v[146:149], v247 offset:1024
	ds_read_b128 v[150:153], v247 offset:2048
	ds_read_b128 v[154:157], v247 offset:3072
	ds_read_b128 v[158:161], v247 offset:16384
	ds_read_b128 v[174:177], v247 offset:17408
	ds_read_b128 v[180:183], v247 offset:18432
	ds_read_b128 v[204:207], v247 offset:19456
	v_lshl_add_u64 v[162:163], s[34:35], 0, v[138:139]
	s_add_i32 m0, s47, 0xc000
	ds_read_b128 v[208:211], v179
	ds_read_b128 v[212:215], v179 offset:1024
	ds_read_b128 v[216:219], v179 offset:2048
	ds_read_b128 v[220:223], v179 offset:3072
	ds_read_b128 v[224:227], v179 offset:4096
	ds_read_b128 v[228:231], v179 offset:5120
	ds_read_b128 v[232:235], v179 offset:6144
	ds_read_b128 v[236:239], v179 offset:7168
	global_load_lds_dwordx4 v[162:163], off
	v_lshl_add_u64 v[162:163], s[34:35], 0, v[140:141]
	s_add_i32 m0, s47, 0xe000
	s_nop 0
	global_load_lds_dwordx4 v[162:163], off
	s_waitcnt vmcnt(8) lgkmcnt(0)
	s_setprio 0
	s_barrier
	v_mfma_f32_16x16x32_bf16 v[128:131], v[142:145], v[208:211], v[128:131]
	v_mfma_f32_16x16x32_bf16 v[124:127], v[150:153], v[208:211], v[124:127]
	v_mfma_f32_16x16x32_bf16 v[112:115], v[142:145], v[216:219], v[112:115]
	v_mfma_f32_16x16x32_bf16 v[108:111], v[150:153], v[216:219], v[108:111]
	v_mfma_f32_16x16x32_bf16 v[96:99], v[142:145], v[224:227], v[96:99]
	v_mfma_f32_16x16x32_bf16 v[92:95], v[150:153], v[224:227], v[92:95]
	v_mfma_f32_16x16x32_bf16 v[80:83], v[142:145], v[232:235], v[80:83]
	v_mfma_f32_16x16x32_bf16 v[76:79], v[150:153], v[232:235], v[76:79]
	v_mfma_f32_16x16x32_bf16 v[128:131], v[146:149], v[212:215], v[128:131]
	v_mfma_f32_16x16x32_bf16 v[124:127], v[154:157], v[212:215], v[124:127]
	v_mfma_f32_16x16x32_bf16 v[112:115], v[146:149], v[220:223], v[112:115]
	v_mfma_f32_16x16x32_bf16 v[108:111], v[154:157], v[220:223], v[108:111]
	v_mfma_f32_16x16x32_bf16 v[96:99], v[146:149], v[228:231], v[96:99]
	v_mfma_f32_16x16x32_bf16 v[92:95], v[154:157], v[228:231], v[92:95]
	v_mfma_f32_16x16x32_bf16 v[80:83], v[146:149], v[236:239], v[80:83]
	v_mfma_f32_16x16x32_bf16 v[76:79], v[154:157], v[236:239], v[76:79]
	v_mfma_f32_16x16x32_bf16 v[120:123], v[158:161], v[208:211], v[120:123]
	v_mfma_f32_16x16x32_bf16 v[116:119], v[180:183], v[208:211], v[116:119]
	v_mfma_f32_16x16x32_bf16 v[104:107], v[158:161], v[216:219], v[104:107]
	v_mfma_f32_16x16x32_bf16 v[100:103], v[180:183], v[216:219], v[100:103]
	v_mfma_f32_16x16x32_bf16 v[88:91], v[158:161], v[224:227], v[88:91]
	v_mfma_f32_16x16x32_bf16 v[84:87], v[180:183], v[224:227], v[84:87]
	v_mfma_f32_16x16x32_bf16 v[72:75], v[158:161], v[232:235], v[72:75]
	v_mfma_f32_16x16x32_bf16 v[68:71], v[180:183], v[232:235], v[68:71]
	v_mfma_f32_16x16x32_bf16 v[120:123], v[174:177], v[212:215], v[120:123]
	v_mfma_f32_16x16x32_bf16 v[116:119], v[204:207], v[212:215], v[116:119]
	v_mfma_f32_16x16x32_bf16 v[104:107], v[174:177], v[220:223], v[104:107]
	v_mfma_f32_16x16x32_bf16 v[100:103], v[204:207], v[220:223], v[100:103]
	v_mfma_f32_16x16x32_bf16 v[88:91], v[174:177], v[228:231], v[88:91]
	v_mfma_f32_16x16x32_bf16 v[84:87], v[204:207], v[228:231], v[84:87]
	v_mfma_f32_16x16x32_bf16 v[72:75], v[174:177], v[236:239], v[72:75]
	v_mfma_f32_16x16x32_bf16 v[68:71], v[204:207], v[236:239], v[68:71]
	s_setprio 3
	s_barrier
	s_add_i32 s34, s64, s46
	s_mov_b32 m0, s34
	ds_read_b128 v[208:211], v179 offset:16384
	ds_read_b128 v[212:215], v179 offset:17408
	ds_read_b128 v[216:219], v179 offset:18432
	ds_read_b128 v[220:223], v179 offset:19456
	ds_read_b128 v[224:227], v179 offset:20480
	ds_read_b128 v[228:231], v179 offset:21504
	ds_read_b128 v[232:235], v179 offset:22528
	ds_read_b128 v[236:239], v179 offset:23552
	global_load_lds_dwordx4 v2, s[38:39]
	s_add_i32 m0, s34, 0x2000
	s_add_u32 s34, s38, 0x158000
	s_addc_u32 s35, s39, 0
	s_add_i32 s64, s65, s46
	global_load_lds_dwordx4 v132, s[38:39]
	s_mov_b32 m0, s64
	s_nop 0
	global_load_lds_dwordx4 v2, s[34:35]
	s_add_i32 m0, s64, 0x2000
	s_nop 0
	global_load_lds_dwordx4 v132, s[34:35]
	s_mov_b32 m0, s47
	s_nop 0
	global_load_lds_dwordx4 v2, s[40:41]
	s_mov_b32 m0, s48
	s_nop 0
	global_load_lds_dwordx4 v132, s[40:41]
	s_waitcnt vmcnt(8) lgkmcnt(0)
	s_setprio 0
	s_barrier
	v_mfma_f32_16x16x32_bf16 v[64:67], v[142:145], v[208:211], v[64:67]
	v_mfma_f32_16x16x32_bf16 v[60:63], v[150:153], v[208:211], v[60:63]
	v_mfma_f32_16x16x32_bf16 v[48:51], v[142:145], v[216:219], v[48:51]
	v_mfma_f32_16x16x32_bf16 v[44:47], v[150:153], v[216:219], v[44:47]
	v_mfma_f32_16x16x32_bf16 v[32:35], v[142:145], v[224:227], v[32:35]
	v_mfma_f32_16x16x32_bf16 v[28:31], v[150:153], v[224:227], v[28:31]
	v_mfma_f32_16x16x32_bf16 v[16:19], v[142:145], v[232:235], v[16:19]
	v_mfma_f32_16x16x32_bf16 v[12:15], v[150:153], v[232:235], v[12:15]
	v_mfma_f32_16x16x32_bf16 v[64:67], v[146:149], v[212:215], v[64:67]
	v_mfma_f32_16x16x32_bf16 v[60:63], v[154:157], v[212:215], v[60:63]
	v_mfma_f32_16x16x32_bf16 v[48:51], v[146:149], v[220:223], v[48:51]
	v_mfma_f32_16x16x32_bf16 v[44:47], v[154:157], v[220:223], v[44:47]
	v_mfma_f32_16x16x32_bf16 v[32:35], v[146:149], v[228:231], v[32:35]
	v_mfma_f32_16x16x32_bf16 v[28:31], v[154:157], v[228:231], v[28:31]
	v_mfma_f32_16x16x32_bf16 v[16:19], v[146:149], v[236:239], v[16:19]
	v_mfma_f32_16x16x32_bf16 v[12:15], v[154:157], v[236:239], v[12:15]
	v_mfma_f32_16x16x32_bf16 v[56:59], v[158:161], v[208:211], v[56:59]
	v_mfma_f32_16x16x32_bf16 v[52:55], v[180:183], v[208:211], v[52:55]
	v_mfma_f32_16x16x32_bf16 v[40:43], v[158:161], v[216:219], v[40:43]
	v_mfma_f32_16x16x32_bf16 v[36:39], v[180:183], v[216:219], v[36:39]
	v_mfma_f32_16x16x32_bf16 v[24:27], v[158:161], v[224:227], v[24:27]
	v_mfma_f32_16x16x32_bf16 v[20:23], v[180:183], v[224:227], v[20:23]
	v_mfma_f32_16x16x32_bf16 v[8:11], v[158:161], v[232:235], v[8:11]
	v_mfma_f32_16x16x32_bf16 v[4:7], v[180:183], v[232:235], v[4:7]
	v_mfma_f32_16x16x32_bf16 v[56:59], v[174:177], v[212:215], v[56:59]
	v_mfma_f32_16x16x32_bf16 v[52:55], v[204:207], v[212:215], v[52:55]
	v_mfma_f32_16x16x32_bf16 v[40:43], v[174:177], v[220:223], v[40:43]
	v_mfma_f32_16x16x32_bf16 v[36:39], v[204:207], v[220:223], v[36:39]
	v_mfma_f32_16x16x32_bf16 v[24:27], v[174:177], v[228:231], v[24:27]
	v_mfma_f32_16x16x32_bf16 v[20:23], v[204:207], v[228:231], v[20:23]
	v_mfma_f32_16x16x32_bf16 v[8:11], v[174:177], v[236:239], v[8:11]
	v_mfma_f32_16x16x32_bf16 v[4:7], v[204:207], v[236:239], v[4:7]
	s_setprio 3
	s_barrier
; #define PG8_STAGE(bufoff, gbase, voff) do { _Pragma("unroll") for (int _i = 0; _i < 2; ++_i) \
;         __builtin_amdgcn_global_load_lds((const unsigned*)((const char*)(gbase) + (voff)[_i]), (PG8_LAS unsigned*)(lds + (bufoff) + ldsw + _i * 8192), 16, 0, 0); } while (0)
; #define PG8_LDA(dst, b, h) do { _Pragma("unroll") for (int m = 0; m < 4; ++m) _Pragma("unroll") for (int k = 0; k < 2; ++k) dst[m][k] = *(const PG8_LAS bf16x8*)(lds + PG8_SA(b, h) + aoff + m * 2048 + k * 1024); } while (0)
; #define PG8_LDB(dst, b, h) do { _Pragma("unroll") for (int n = 0; n < 2; ++n) _Pragma("unroll") for (int k = 0; k < 2; ++k) dst[n][k] = *(const PG8_LAS bf16x8*)(lds + PG8_SB(b, h) + boff + n * 2048 + k * 1024); } while (0)
; #define PG8_MMA(ai, bj, At, Bt) do { __builtin_amdgcn_s_setprio(1); _Pragma("unroll") for (int m = 0; m < 4; ++m) _Pragma("unroll") for (int n = 0; n < 2; ++n) _Pragma("unroll") for (int k = 0; k < 2; ++k) \
;         acc[ai][bj][m][n] = __builtin_amdgcn_mfma_f32_16x16x32_bf16(Bt[n][k], At[m][k], acc[ai][bj][m][n], 0, 0, 0); __builtin_amdgcn_s_setprio(0); } while (0)
; #define PG8_WAIT_V(n) asm volatile("s_waitcnt vmcnt(" #n ")" ::: "memory")
; #define PG8_WAIT_L(n) asm volatile("s_waitcnt lgkmcnt(" #n ")" ::: "memory")
; #define PG8_BAR __builtin_amdgcn_s_barrier()
; #define PG8_SCHED __builtin_amdgcn_sched_barrier(0)
; template <class Epi, class Sched, bool ALIGN_EPI = false, bool SP2 = false>
; __device__ __forceinline__ void gemm_phase(PG8_LAS unsigned char* lds, const Gemm g, const Sched& S, const Epi& E) {
;     ...
;             PG8_LDB(B0, 1, 0); PG8_LDB(B1, 1, 1); PG8_SCHED; PG8_LDA(At, 1, 0); PG8_STAGE(PG8_SA(0, 1), a2 + hstep, voffA);
;             PG8_WAIT_V(8); PG8_WAIT_L(0); PG8_BAR; PG8_MMA(0, 0, At, B0); PG8_MMA(0, 1, At, B1); PG8_BAR; PG8_SCHED;
;             PG8_LDA(At, 1, 1); PG8_STAGE(PG8_SB(1, 0), b3, voffB); PG8_STAGE(PG8_SB(1, 1), b3 + hstep, voffB); PG8_STAGE(PG8_SA(1, 0), a3, voffA);
;             PG8_WAIT_V(8); PG8_WAIT_L(0); PG8_BAR; PG8_MMA(1, 0, At, B0); PG8_MMA(1, 1, At, B1); PG8_BAR; PG8_SCHED;
	s_add_i32 s64, 0, 0x18000
	s_add_i32 s65, 0, 0x1c000
	ds_read_b128 v[142:145], v247 offset:32768
	ds_read_b128 v[146:149], v247 offset:33792
	ds_read_b128 v[150:153], v247 offset:34816
	ds_read_b128 v[154:157], v247 offset:35840
	ds_read_b128 v[158:161], v247 offset:49152
	ds_read_b128 v[174:177], v247 offset:50176
	ds_read_b128 v[180:183], v247 offset:51200
	ds_read_b128 v[204:207], v247 offset:52224
	s_add_u32 s34, s40, 0x158000
	s_addc_u32 s35, s41, 0
	s_mov_b32 m0, s49
	ds_read_b128 v[208:211], v179 offset:32768
	ds_read_b128 v[212:215], v179 offset:33792
	ds_read_b128 v[216:219], v179 offset:34816
	ds_read_b128 v[220:223], v179 offset:35840
	ds_read_b128 v[224:227], v179 offset:36864
	ds_read_b128 v[228:231], v179 offset:37888
	ds_read_b128 v[232:235], v179 offset:38912
	ds_read_b128 v[236:239], v179 offset:39936
	global_load_lds_dwordx4 v2, s[34:35]
	s_mov_b32 m0, s50
	s_nop 0
	global_load_lds_dwordx4 v132, s[34:35]
	s_nop 0
	s_waitcnt vmcnt(8) lgkmcnt(0)
	s_setprio 0
	s_barrier
	v_mfma_f32_16x16x32_bf16 v[128:131], v[142:145], v[208:211], v[128:131]
	v_mfma_f32_16x16x32_bf16 v[124:127], v[150:153], v[208:211], v[124:127]
	v_mfma_f32_16x16x32_bf16 v[112:115], v[142:145], v[216:219], v[112:115]
	v_mfma_f32_16x16x32_bf16 v[108:111], v[150:153], v[216:219], v[108:111]
	v_mfma_f32_16x16x32_bf16 v[96:99], v[142:145], v[224:227], v[96:99]
	v_mfma_f32_16x16x32_bf16 v[92:95], v[150:153], v[224:227], v[92:95]
	v_mfma_f32_16x16x32_bf16 v[80:83], v[142:145], v[232:235], v[80:83]
	v_mfma_f32_16x16x32_bf16 v[76:79], v[150:153], v[232:235], v[76:79]
	v_mfma_f32_16x16x32_bf16 v[128:131], v[146:149], v[212:215], v[128:131]
	v_mfma_f32_16x16x32_bf16 v[124:127], v[154:157], v[212:215], v[124:127]
	v_mfma_f32_16x16x32_bf16 v[112:115], v[146:149], v[220:223], v[112:115]
	v_mfma_f32_16x16x32_bf16 v[108:111], v[154:157], v[220:223], v[108:111]
	v_mfma_f32_16x16x32_bf16 v[96:99], v[146:149], v[228:231], v[96:99]
	v_mfma_f32_16x16x32_bf16 v[92:95], v[154:157], v[228:231], v[92:95]
	v_mfma_f32_16x16x32_bf16 v[80:83], v[146:149], v[236:239], v[80:83]
	v_mfma_f32_16x16x32_bf16 v[76:79], v[154:157], v[236:239], v[76:79]
	v_mfma_f32_16x16x32_bf16 v[120:123], v[158:161], v[208:211], v[120:123]
	v_mfma_f32_16x16x32_bf16 v[116:119], v[180:183], v[208:211], v[116:119]
	v_mfma_f32_16x16x32_bf16 v[104:107], v[158:161], v[216:219], v[104:107]
	v_mfma_f32_16x16x32_bf16 v[100:103], v[180:183], v[216:219], v[100:103]
	v_mfma_f32_16x16x32_bf16 v[88:91], v[158:161], v[224:227], v[88:91]
	v_mfma_f32_16x16x32_bf16 v[84:87], v[180:183], v[224:227], v[84:87]
	v_mfma_f32_16x16x32_bf16 v[72:75], v[158:161], v[232:235], v[72:75]
	v_mfma_f32_16x16x32_bf16 v[68:71], v[180:183], v[232:235], v[68:71]
	v_mfma_f32_16x16x32_bf16 v[120:123], v[174:177], v[212:215], v[120:123]
	v_mfma_f32_16x16x32_bf16 v[116:119], v[204:207], v[212:215], v[116:119]
	v_mfma_f32_16x16x32_bf16 v[104:107], v[174:177], v[220:223], v[104:107]
	v_mfma_f32_16x16x32_bf16 v[100:103], v[204:207], v[220:223], v[100:103]
	v_mfma_f32_16x16x32_bf16 v[88:91], v[174:177], v[228:231], v[88:91]
	v_mfma_f32_16x16x32_bf16 v[84:87], v[204:207], v[228:231], v[84:87]
	v_mfma_f32_16x16x32_bf16 v[72:75], v[174:177], v[236:239], v[72:75]
	v_mfma_f32_16x16x32_bf16 v[68:71], v[204:207], v[236:239], v[68:71]
	s_setprio 3
	s_barrier
	s_add_i32 s34, s64, s46
	s_add_i32 m0, s34, 0xffffff80
	ds_read_b128 v[208:211], v179 offset:49152
	ds_read_b128 v[212:215], v179 offset:50176
	ds_read_b128 v[216:219], v179 offset:51200
	ds_read_b128 v[220:223], v179 offset:52224
	ds_read_b128 v[224:227], v179 offset:53248
	ds_read_b128 v[228:231], v179 offset:54272
	ds_read_b128 v[232:235], v179 offset:55296
	ds_read_b128 v[236:239], v179 offset:56320
	global_load_lds_dwordx4 v2, s[38:39] offset:128
	s_add_i32 m0, s34, 0x1f80
	s_add_u32 s34, s38, 0x158080
	s_addc_u32 s35, s39, 0
	global_load_lds_dwordx4 v132, s[38:39] offset:128
	s_add_i32 s38, s65, s46
	s_mov_b32 m0, s38
	s_nop 0
	global_load_lds_dwordx4 v2, s[34:35]
	s_add_i32 m0, s38, 0x2000
	s_nop 0
	global_load_lds_dwordx4 v132, s[34:35]
	s_add_i32 m0, s53, 0xffffff80
	s_nop 0
	global_load_lds_dwordx4 v2, s[40:41] offset:128
	s_add_i32 m0, s54, 0xffffff80
	s_nop 0
	global_load_lds_dwordx4 v132, s[40:41] offset:128
	s_nop 0
	s_waitcnt vmcnt(8) lgkmcnt(0)
	s_setprio 0
	s_barrier
	v_mfma_f32_16x16x32_bf16 v[64:67], v[142:145], v[208:211], v[64:67]
	v_mfma_f32_16x16x32_bf16 v[60:63], v[150:153], v[208:211], v[60:63]
	v_mfma_f32_16x16x32_bf16 v[48:51], v[142:145], v[216:219], v[48:51]
	v_mfma_f32_16x16x32_bf16 v[44:47], v[150:153], v[216:219], v[44:47]
	v_mfma_f32_16x16x32_bf16 v[32:35], v[142:145], v[224:227], v[32:35]
	v_mfma_f32_16x16x32_bf16 v[28:31], v[150:153], v[224:227], v[28:31]
	v_mfma_f32_16x16x32_bf16 v[16:19], v[142:145], v[232:235], v[16:19]
	v_mfma_f32_16x16x32_bf16 v[12:15], v[150:153], v[232:235], v[12:15]
	v_mfma_f32_16x16x32_bf16 v[64:67], v[146:149], v[212:215], v[64:67]
	v_mfma_f32_16x16x32_bf16 v[60:63], v[154:157], v[212:215], v[60:63]
	v_mfma_f32_16x16x32_bf16 v[48:51], v[146:149], v[220:223], v[48:51]
	v_mfma_f32_16x16x32_bf16 v[44:47], v[154:157], v[220:223], v[44:47]
	v_mfma_f32_16x16x32_bf16 v[32:35], v[146:149], v[228:231], v[32:35]
	v_mfma_f32_16x16x32_bf16 v[28:31], v[154:157], v[228:231], v[28:31]
	v_mfma_f32_16x16x32_bf16 v[16:19], v[146:149], v[236:239], v[16:19]
	v_mfma_f32_16x16x32_bf16 v[12:15], v[154:157], v[236:239], v[12:15]
	v_mfma_f32_16x16x32_bf16 v[56:59], v[158:161], v[208:211], v[56:59]
	v_mfma_f32_16x16x32_bf16 v[52:55], v[180:183], v[208:211], v[52:55]
	v_mfma_f32_16x16x32_bf16 v[40:43], v[158:161], v[216:219], v[40:43]
	v_mfma_f32_16x16x32_bf16 v[36:39], v[180:183], v[216:219], v[36:39]
	v_mfma_f32_16x16x32_bf16 v[24:27], v[158:161], v[224:227], v[24:27]
	v_mfma_f32_16x16x32_bf16 v[20:23], v[180:183], v[224:227], v[20:23]
	v_mfma_f32_16x16x32_bf16 v[8:11], v[158:161], v[232:235], v[8:11]
	v_mfma_f32_16x16x32_bf16 v[4:7], v[180:183], v[232:235], v[4:7]
	v_mfma_f32_16x16x32_bf16 v[56:59], v[174:177], v[212:215], v[56:59]
	v_mfma_f32_16x16x32_bf16 v[52:55], v[204:207], v[212:215], v[52:55]
	v_mfma_f32_16x16x32_bf16 v[40:43], v[174:177], v[220:223], v[40:43]
	v_mfma_f32_16x16x32_bf16 v[36:39], v[204:207], v[220:223], v[36:39]
	v_mfma_f32_16x16x32_bf16 v[24:27], v[174:177], v[228:231], v[24:27]
	v_mfma_f32_16x16x32_bf16 v[20:23], v[204:207], v[228:231], v[20:23]
	v_mfma_f32_16x16x32_bf16 v[8:11], v[174:177], v[236:239], v[8:11]
	v_mfma_f32_16x16x32_bf16 v[4:7], v[204:207], v[236:239], v[4:7]
	s_setprio 3
	s_barrier
	s_add_i32 s63, s63, 2
	s_add_u32 s61, s61, 0x100
	s_addc_u32 s62, s62, 0
	s_cmpk_gt_u32 s63, 0x53
	s_mov_b64 s[34:35], s[36:37]
	s_cbranch_scc0 .LBB0_575
	s_and_b64 vcc, exec, s[28:29]
	s_cbranch_vccz .LBB0_578
	s_barrier

; #define PG8_STAGE(bufoff, gbase, voff) do { _Pragma("unroll") for (int _i = 0; _i < 2; ++_i) \
;         __builtin_amdgcn_global_load_lds((const unsigned*)((const char*)(gbase) + (voff)[_i]), (PG8_LAS unsigned*)(lds + (bufoff) + ldsw + _i * 8192), 16, 0, 0); } while (0)
; #define PG8_LDA(dst, b, h) do { _Pragma("unroll") for (int m = 0; m < 4; ++m) _Pragma("unroll") for (int k = 0; k < 2; ++k) dst[m][k] = *(const PG8_LAS bf16x8*)(lds + PG8_SA(b, h) + aoff + m * 2048 + k * 1024); } while (0)
; #define PG8_LDB(dst, b, h) do { _Pragma("unroll") for (int n = 0; n < 2; ++n) _Pragma("unroll") for (int k = 0; k < 2; ++k) dst[n][k] = *(const PG8_LAS bf16x8*)(lds + PG8_SB(b, h) + boff + n * 2048 + k * 1024); } while (0)
; #define PG8_MMA(ai, bj, At, Bt) do { __builtin_amdgcn_s_setprio(1); _Pragma("unroll") for (int m = 0; m < 4; ++m) _Pragma("unroll") for (int n = 0; n < 2; ++n) _Pragma("unroll") for (int k = 0; k < 2; ++k) \
;         acc[ai][bj][m][n] = __builtin_amdgcn_mfma_f32_16x16x32_bf16(Bt[n][k], At[m][k], acc[ai][bj][m][n], 0, 0, 0); __builtin_amdgcn_s_setprio(0); } while (0)
; #define PG8_WAIT_V(n) asm volatile("s_waitcnt vmcnt(" #n ")" ::: "memory")
; #define PG8_WAIT_L(n) asm volatile("s_waitcnt lgkmcnt(" #n ")" ::: "memory")
; #define PG8_BAR __builtin_amdgcn_s_barrier()
; #define PG8_SCHED __builtin_amdgcn_sched_barrier(0)
; template <class Epi, class Sched, bool ALIGN_EPI = false, bool SP2 = false>
; __device__ __forceinline__ void gemm_phase(PG8_LAS unsigned char* lds, const Gemm g, const Sched& S, const Epi& E) {
;     ...
;             PG8_LDB(B0, 0, 0); PG8_LDB(B1, 0, 1); PG8_SCHED; PG8_LDA(At, 0, 0); PG8_STAGE(PG8_SA(1, 1), a1 + hstep, voffA);
;             PG8_WAIT_V(8); PG8_WAIT_L(0); PG8_BAR; PG8_MMA(0, 0, At, B0); PG8_MMA(0, 1, At, B1); PG8_BAR; PG8_SCHED;
;             PG8_LDA(At, 0, 1); PG8_STAGE(PG8_SB(0, 0), b2, voffB); PG8_STAGE(PG8_SB(0, 1), b2 + hstep, voffB); PG8_STAGE(PG8_SA(0, 0), a2, voffA);
;             PG8_WAIT_V(8); PG8_WAIT_L(0); PG8_BAR; PG8_MMA(1, 0, At, B0); PG8_MMA(1, 1, At, B1); PG8_BAR; PG8_SCHED;
.LBB0_674:
	s_add_u32 s42, s40, 0xfff80080
	s_addc_u32 s43, s41, -1
	s_add_i32 s64, 0, 0x10000
	s_cmp_eq_u32 s63, 28
	s_cselect_b32 s45, s5, s43
	s_cselect_b32 s44, s4, s42
	s_cselect_b32 s43, s37, s62
	s_cselect_b32 s42, s36, s35
	s_add_i32 s66, 0, 0x14000
	ds_read_b128 v[132:135], v249
	ds_read_b128 v[136:139], v249 offset:1024
	ds_read_b128 v[140:143], v249 offset:2048
	ds_read_b128 v[144:147], v249 offset:3072
	ds_read_b128 v[158:161], v249 offset:16384
	ds_read_b128 v[174:177], v249 offset:17408
	ds_read_b128 v[206:209], v249 offset:18432
	ds_read_b128 v[210:213], v249 offset:19456
	s_add_i32 m0, s39, 0xc000
	ds_read_b128 v[214:217], v204
	ds_read_b128 v[218:221], v204 offset:1024
	ds_read_b128 v[222:225], v204 offset:2048
	ds_read_b128 v[226:229], v204 offset:3072
	ds_read_b128 v[230:233], v204 offset:4096
	ds_read_b128 v[234:237], v204 offset:5120
	ds_read_b128 v[238:241], v204 offset:6144
	ds_read_b128 v[242:245], v204 offset:7168
	global_load_lds_dwordx4 v154, s[40:41]
	s_add_i32 m0, s39, 0xe000
	s_nop 0
	global_load_lds_dwordx4 v156, s[40:41]
	s_waitcnt vmcnt(8) lgkmcnt(0)
	s_setprio 0
	s_barrier
	v_mfma_f32_16x16x32_bf16 v[128:131], v[132:135], v[214:217], v[128:131]
	v_mfma_f32_16x16x32_bf16 v[124:127], v[140:143], v[214:217], v[124:127]
	v_mfma_f32_16x16x32_bf16 v[116:119], v[132:135], v[222:225], v[116:119]
	v_mfma_f32_16x16x32_bf16 v[108:111], v[140:143], v[222:225], v[108:111]
	v_mfma_f32_16x16x32_bf16 v[100:103], v[132:135], v[230:233], v[100:103]
	v_mfma_f32_16x16x32_bf16 v[92:95], v[140:143], v[230:233], v[92:95]
	v_mfma_f32_16x16x32_bf16 v[84:87], v[132:135], v[238:241], v[84:87]
	v_mfma_f32_16x16x32_bf16 v[76:79], v[140:143], v[238:241], v[76:79]
	v_mfma_f32_16x16x32_bf16 v[128:131], v[136:139], v[218:221], v[128:131]
	v_mfma_f32_16x16x32_bf16 v[124:127], v[144:147], v[218:221], v[124:127]
	v_mfma_f32_16x16x32_bf16 v[116:119], v[136:139], v[226:229], v[116:119]
	v_mfma_f32_16x16x32_bf16 v[108:111], v[144:147], v[226:229], v[108:111]
	v_mfma_f32_16x16x32_bf16 v[100:103], v[136:139], v[234:237], v[100:103]
	v_mfma_f32_16x16x32_bf16 v[92:95], v[144:147], v[234:237], v[92:95]
	v_mfma_f32_16x16x32_bf16 v[84:87], v[136:139], v[242:245], v[84:87]
	v_mfma_f32_16x16x32_bf16 v[76:79], v[144:147], v[242:245], v[76:79]
	v_mfma_f32_16x16x32_bf16 v[120:123], v[158:161], v[214:217], v[120:123]
	v_mfma_f32_16x16x32_bf16 v[112:115], v[206:209], v[214:217], v[112:115]
	v_mfma_f32_16x16x32_bf16 v[104:107], v[158:161], v[222:225], v[104:107]
	v_mfma_f32_16x16x32_bf16 v[96:99], v[206:209], v[222:225], v[96:99]
	v_mfma_f32_16x16x32_bf16 v[88:91], v[158:161], v[230:233], v[88:91]
	v_mfma_f32_16x16x32_bf16 v[80:83], v[206:209], v[230:233], v[80:83]
	v_mfma_f32_16x16x32_bf16 v[72:75], v[158:161], v[238:241], v[72:75]
	v_mfma_f32_16x16x32_bf16 v[68:71], v[206:209], v[238:241], v[68:71]
	v_mfma_f32_16x16x32_bf16 v[120:123], v[174:177], v[218:221], v[120:123]
	v_mfma_f32_16x16x32_bf16 v[112:115], v[210:213], v[218:221], v[112:115]
	v_mfma_f32_16x16x32_bf16 v[104:107], v[174:177], v[226:229], v[104:107]
	v_mfma_f32_16x16x32_bf16 v[96:99], v[210:213], v[226:229], v[96:99]
	v_mfma_f32_16x16x32_bf16 v[88:91], v[174:177], v[234:237], v[88:91]
	v_mfma_f32_16x16x32_bf16 v[80:83], v[210:213], v[234:237], v[80:83]
	v_mfma_f32_16x16x32_bf16 v[72:75], v[174:177], v[242:245], v[72:75]
	v_mfma_f32_16x16x32_bf16 v[68:71], v[210:213], v[242:245], v[68:71]
	s_setprio 3
	s_barrier
	s_add_i32 s64, s64, s46
	s_mov_b32 m0, s64
	ds_read_b128 v[214:217], v204 offset:16384
	ds_read_b128 v[218:221], v204 offset:17408
	ds_read_b128 v[222:225], v204 offset:18432
	ds_read_b128 v[226:229], v204 offset:19456
	ds_read_b128 v[230:233], v204 offset:20480
	ds_read_b128 v[234:237], v204 offset:21504
	ds_read_b128 v[238:241], v204 offset:22528
	ds_read_b128 v[242:245], v204 offset:23552
	global_load_lds_dwordx4 v2, s[42:43]
	s_add_i32 m0, s64, 0x2000
	s_add_u32 s64, s42, 0x80000
	s_addc_u32 s65, s43, 0
	s_add_i32 s66, s66, s46
	global_load_lds_dwordx4 v148, s[42:43]
	s_mov_b32 m0, s66
	s_nop 0
	global_load_lds_dwordx4 v2, s[64:65]
	s_add_i32 m0, s66, 0x2000
	s_nop 0
	global_load_lds_dwordx4 v148, s[64:65]
	s_mov_b32 m0, s39
	s_nop 0
	global_load_lds_dwordx4 v152, s[44:45]
	s_mov_b32 m0, s51
	s_nop 0
	global_load_lds_dwordx4 v150, s[44:45]
	s_waitcnt vmcnt(8) lgkmcnt(0)
	s_setprio 0
	s_barrier
	v_mfma_f32_16x16x32_bf16 v[64:67], v[132:135], v[214:217], v[64:67]
	v_mfma_f32_16x16x32_bf16 v[60:63], v[140:143], v[214:217], v[60:63]
	v_mfma_f32_16x16x32_bf16 v[52:55], v[132:135], v[222:225], v[52:55]
	v_mfma_f32_16x16x32_bf16 v[44:47], v[140:143], v[222:225], v[44:47]
	v_mfma_f32_16x16x32_bf16 v[36:39], v[132:135], v[230:233], v[36:39]
	v_mfma_f32_16x16x32_bf16 v[28:31], v[140:143], v[230:233], v[28:31]
	v_mfma_f32_16x16x32_bf16 v[20:23], v[132:135], v[238:241], v[20:23]
	v_mfma_f32_16x16x32_bf16 v[12:15], v[140:143], v[238:241], v[12:15]
	v_mfma_f32_16x16x32_bf16 v[64:67], v[136:139], v[218:221], v[64:67]
	v_mfma_f32_16x16x32_bf16 v[60:63], v[144:147], v[218:221], v[60:63]
	v_mfma_f32_16x16x32_bf16 v[52:55], v[136:139], v[226:229], v[52:55]
	v_mfma_f32_16x16x32_bf16 v[44:47], v[144:147], v[226:229], v[44:47]
	v_mfma_f32_16x16x32_bf16 v[36:39], v[136:139], v[234:237], v[36:39]
	v_mfma_f32_16x16x32_bf16 v[28:31], v[144:147], v[234:237], v[28:31]
	v_mfma_f32_16x16x32_bf16 v[20:23], v[136:139], v[242:245], v[20:23]
	v_mfma_f32_16x16x32_bf16 v[12:15], v[144:147], v[242:245], v[12:15]
	v_mfma_f32_16x16x32_bf16 v[56:59], v[158:161], v[214:217], v[56:59]
	v_mfma_f32_16x16x32_bf16 v[48:51], v[206:209], v[214:217], v[48:51]
	v_mfma_f32_16x16x32_bf16 v[40:43], v[158:161], v[222:225], v[40:43]
	v_mfma_f32_16x16x32_bf16 v[32:35], v[206:209], v[222:225], v[32:35]
	v_mfma_f32_16x16x32_bf16 v[24:27], v[158:161], v[230:233], v[24:27]
	v_mfma_f32_16x16x32_bf16 v[16:19], v[206:209], v[230:233], v[16:19]
	v_mfma_f32_16x16x32_bf16 v[8:11], v[158:161], v[238:241], v[8:11]
	v_mfma_f32_16x16x32_bf16 v[4:7], v[206:209], v[238:241], v[4:7]
	v_mfma_f32_16x16x32_bf16 v[56:59], v[174:177], v[218:221], v[56:59]
	v_mfma_f32_16x16x32_bf16 v[48:51], v[210:213], v[218:221], v[48:51]
	v_mfma_f32_16x16x32_bf16 v[40:43], v[174:177], v[226:229], v[40:43]
	v_mfma_f32_16x16x32_bf16 v[32:35], v[210:213], v[226:229], v[32:35]
	v_mfma_f32_16x16x32_bf16 v[24:27], v[174:177], v[234:237], v[24:27]
	v_mfma_f32_16x16x32_bf16 v[16:19], v[210:213], v[234:237], v[16:19]
	v_mfma_f32_16x16x32_bf16 v[8:11], v[174:177], v[242:245], v[8:11]
	v_mfma_f32_16x16x32_bf16 v[4:7], v[210:213], v[242:245], v[4:7]
	s_setprio 3
	s_barrier
; #define PG8_STAGE(bufoff, gbase, voff) do { _Pragma("unroll") for (int _i = 0; _i < 2; ++_i) \
;         __builtin_amdgcn_global_load_lds((const unsigned*)((const char*)(gbase) + (voff)[_i]), (PG8_LAS unsigned*)(lds + (bufoff) + ldsw + _i * 8192), 16, 0, 0); } while (0)
; #define PG8_LDA(dst, b, h) do { _Pragma("unroll") for (int m = 0; m < 4; ++m) _Pragma("unroll") for (int k = 0; k < 2; ++k) dst[m][k] = *(const PG8_LAS bf16x8*)(lds + PG8_SA(b, h) + aoff + m * 2048 + k * 1024); } while (0)
; #define PG8_LDB(dst, b, h) do { _Pragma("unroll") for (int n = 0; n < 2; ++n) _Pragma("unroll") for (int k = 0; k < 2; ++k) dst[n][k] = *(const PG8_LAS bf16x8*)(lds + PG8_SB(b, h) + boff + n * 2048 + k * 1024); } while (0)
; #define PG8_MMA(ai, bj, At, Bt) do { __builtin_amdgcn_s_setprio(1); _Pragma("unroll") for (int m = 0; m < 4; ++m) _Pragma("unroll") for (int n = 0; n < 2; ++n) _Pragma("unroll") for (int k = 0; k < 2; ++k) \
;         acc[ai][bj][m][n] = __builtin_amdgcn_mfma_f32_16x16x32_bf16(Bt[n][k], At[m][k], acc[ai][bj][m][n], 0, 0, 0); __builtin_amdgcn_s_setprio(0); } while (0)
; #define PG8_WAIT_V(n) asm volatile("s_waitcnt vmcnt(" #n ")" ::: "memory")
; #define PG8_WAIT_L(n) asm volatile("s_waitcnt lgkmcnt(" #n ")" ::: "memory")
; #define PG8_BAR __builtin_amdgcn_s_barrier()
; #define PG8_SCHED __builtin_amdgcn_sched_barrier(0)
; template <class Epi, class Sched, bool ALIGN_EPI = false, bool SP2 = false>
; __device__ __forceinline__ void gemm_phase(PG8_LAS unsigned char* lds, const Gemm g, const Sched& S, const Epi& E) {
;     ...
;             PG8_LDB(B0, 1, 0); PG8_LDB(B1, 1, 1); PG8_SCHED; PG8_LDA(At, 1, 0); PG8_STAGE(PG8_SA(0, 1), a2 + hstep, voffA);
;             PG8_WAIT_V(8); PG8_WAIT_L(0); PG8_BAR; PG8_MMA(0, 0, At, B0); PG8_MMA(0, 1, At, B1); PG8_BAR; PG8_SCHED;
;             PG8_LDA(At, 1, 1); PG8_STAGE(PG8_SB(1, 0), b3, voffB); PG8_STAGE(PG8_SB(1, 1), b3 + hstep, voffB); PG8_STAGE(PG8_SA(1, 0), a3, voffA);
;             PG8_WAIT_V(8); PG8_WAIT_L(0); PG8_BAR; PG8_MMA(1, 0, At, B0); PG8_MMA(1, 1, At, B1); PG8_BAR; PG8_SCHED;
	s_add_i32 s64, 0, 0x18000
	s_add_i32 s65, 0, 0x1c000
	ds_read_b128 v[132:135], v249 offset:32768
	ds_read_b128 v[136:139], v249 offset:33792
	ds_read_b128 v[140:143], v249 offset:34816
	ds_read_b128 v[144:147], v249 offset:35840
	ds_read_b128 v[158:161], v249 offset:49152
	ds_read_b128 v[174:177], v249 offset:50176
	ds_read_b128 v[206:209], v249 offset:51200
	ds_read_b128 v[210:213], v249 offset:52224
	s_add_u32 s100, s44, 0x80
	s_addc_u32 s101, s45, 0
	s_add_u32 s44, s44, 0x80000
	s_addc_u32 s45, s45, 0
	s_mov_b32 m0, s52
	ds_read_b128 v[214:217], v204 offset:32768
	ds_read_b128 v[218:221], v204 offset:33792
	ds_read_b128 v[222:225], v204 offset:34816
	ds_read_b128 v[226:229], v204 offset:35840
	ds_read_b128 v[230:233], v204 offset:36864
	ds_read_b128 v[234:237], v204 offset:37888
	ds_read_b128 v[238:241], v204 offset:38912
	ds_read_b128 v[242:245], v204 offset:39936
	global_load_lds_dwordx4 v152, s[44:45]
	s_mov_b32 m0, s53
	s_nop 0
	global_load_lds_dwordx4 v150, s[44:45]
	s_waitcnt vmcnt(8) lgkmcnt(0)
	s_setprio 0
	s_barrier
	v_mfma_f32_16x16x32_bf16 v[128:131], v[132:135], v[214:217], v[128:131]
	v_mfma_f32_16x16x32_bf16 v[124:127], v[140:143], v[214:217], v[124:127]
	v_mfma_f32_16x16x32_bf16 v[116:119], v[132:135], v[222:225], v[116:119]
	v_mfma_f32_16x16x32_bf16 v[108:111], v[140:143], v[222:225], v[108:111]
	v_mfma_f32_16x16x32_bf16 v[100:103], v[132:135], v[230:233], v[100:103]
	v_mfma_f32_16x16x32_bf16 v[92:95], v[140:143], v[230:233], v[92:95]
	v_mfma_f32_16x16x32_bf16 v[84:87], v[132:135], v[238:241], v[84:87]
	v_mfma_f32_16x16x32_bf16 v[76:79], v[140:143], v[238:241], v[76:79]
	v_mfma_f32_16x16x32_bf16 v[128:131], v[136:139], v[218:221], v[128:131]
	v_mfma_f32_16x16x32_bf16 v[124:127], v[144:147], v[218:221], v[124:127]
	v_mfma_f32_16x16x32_bf16 v[116:119], v[136:139], v[226:229], v[116:119]
	v_mfma_f32_16x16x32_bf16 v[108:111], v[144:147], v[226:229], v[108:111]
	v_mfma_f32_16x16x32_bf16 v[100:103], v[136:139], v[234:237], v[100:103]
	v_mfma_f32_16x16x32_bf16 v[92:95], v[144:147], v[234:237], v[92:95]
	v_mfma_f32_16x16x32_bf16 v[84:87], v[136:139], v[242:245], v[84:87]
	v_mfma_f32_16x16x32_bf16 v[76:79], v[144:147], v[242:245], v[76:79]
	v_mfma_f32_16x16x32_bf16 v[120:123], v[158:161], v[214:217], v[120:123]
	v_mfma_f32_16x16x32_bf16 v[112:115], v[206:209], v[214:217], v[112:115]
	v_mfma_f32_16x16x32_bf16 v[104:107], v[158:161], v[222:225], v[104:107]
	v_mfma_f32_16x16x32_bf16 v[96:99], v[206:209], v[222:225], v[96:99]
	v_mfma_f32_16x16x32_bf16 v[88:91], v[158:161], v[230:233], v[88:91]
	v_mfma_f32_16x16x32_bf16 v[80:83], v[206:209], v[230:233], v[80:83]
	v_mfma_f32_16x16x32_bf16 v[72:75], v[158:161], v[238:241], v[72:75]
	v_mfma_f32_16x16x32_bf16 v[68:71], v[206:209], v[238:241], v[68:71]
	v_mfma_f32_16x16x32_bf16 v[120:123], v[174:177], v[218:221], v[120:123]
	v_mfma_f32_16x16x32_bf16 v[112:115], v[210:213], v[218:221], v[112:115]
	v_mfma_f32_16x16x32_bf16 v[104:107], v[174:177], v[226:229], v[104:107]
	v_mfma_f32_16x16x32_bf16 v[96:99], v[210:213], v[226:229], v[96:99]
	v_mfma_f32_16x16x32_bf16 v[88:91], v[174:177], v[234:237], v[88:91]
	v_mfma_f32_16x16x32_bf16 v[80:83], v[210:213], v[234:237], v[80:83]
	v_mfma_f32_16x16x32_bf16 v[72:75], v[174:177], v[242:245], v[72:75]
	v_mfma_f32_16x16x32_bf16 v[68:71], v[210:213], v[242:245], v[68:71]
	s_setprio 3
	s_barrier
	s_add_i32 s44, s64, s46
	s_add_i32 m0, s44, 0xffffff80
	ds_read_b128 v[214:217], v204 offset:49152
	ds_read_b128 v[218:221], v204 offset:50176
	ds_read_b128 v[222:225], v204 offset:51200
	ds_read_b128 v[226:229], v204 offset:52224
	ds_read_b128 v[230:233], v204 offset:53248
	ds_read_b128 v[234:237], v204 offset:54272
	ds_read_b128 v[238:241], v204 offset:55296
	ds_read_b128 v[242:245], v204 offset:56320
	global_load_lds_dwordx4 v2, s[42:43] offset:128
	s_add_i32 m0, s44, 0x1f80
	s_add_i32 s44, s65, s46
	global_load_lds_dwordx4 v148, s[42:43] offset:128
	s_add_u32 s42, s42, 0x80080
	s_addc_u32 s43, s43, 0
	s_mov_b32 m0, s44
	s_nop 0
	global_load_lds_dwordx4 v2, s[42:43]
	s_add_i32 m0, s44, 0x2000
	s_nop 0
	global_load_lds_dwordx4 v148, s[42:43]
	s_mov_b32 m0, s54
	s_nop 0
	global_load_lds_dwordx4 v152, s[100:101]
	s_mov_b32 m0, s55
	s_nop 0
	global_load_lds_dwordx4 v150, s[100:101]
	s_nop 0
	s_waitcnt vmcnt(8) lgkmcnt(0)
	s_setprio 0
	s_barrier
	v_mfma_f32_16x16x32_bf16 v[64:67], v[132:135], v[214:217], v[64:67]
	v_mfma_f32_16x16x32_bf16 v[60:63], v[140:143], v[214:217], v[60:63]
	v_mfma_f32_16x16x32_bf16 v[52:55], v[132:135], v[222:225], v[52:55]
	v_mfma_f32_16x16x32_bf16 v[44:47], v[140:143], v[222:225], v[44:47]
	v_mfma_f32_16x16x32_bf16 v[36:39], v[132:135], v[230:233], v[36:39]
	v_mfma_f32_16x16x32_bf16 v[28:31], v[140:143], v[230:233], v[28:31]
	v_mfma_f32_16x16x32_bf16 v[20:23], v[132:135], v[238:241], v[20:23]
	v_mfma_f32_16x16x32_bf16 v[12:15], v[140:143], v[238:241], v[12:15]
	v_mfma_f32_16x16x32_bf16 v[64:67], v[136:139], v[218:221], v[64:67]
	v_mfma_f32_16x16x32_bf16 v[60:63], v[144:147], v[218:221], v[60:63]
	v_mfma_f32_16x16x32_bf16 v[52:55], v[136:139], v[226:229], v[52:55]
	v_mfma_f32_16x16x32_bf16 v[44:47], v[144:147], v[226:229], v[44:47]
	v_mfma_f32_16x16x32_bf16 v[36:39], v[136:139], v[234:237], v[36:39]
	v_mfma_f32_16x16x32_bf16 v[28:31], v[144:147], v[234:237], v[28:31]
	v_mfma_f32_16x16x32_bf16 v[20:23], v[136:139], v[242:245], v[20:23]
	v_mfma_f32_16x16x32_bf16 v[12:15], v[144:147], v[242:245], v[12:15]
	v_mfma_f32_16x16x32_bf16 v[56:59], v[158:161], v[214:217], v[56:59]
	v_mfma_f32_16x16x32_bf16 v[48:51], v[206:209], v[214:217], v[48:51]
	v_mfma_f32_16x16x32_bf16 v[40:43], v[158:161], v[222:225], v[40:43]
	v_mfma_f32_16x16x32_bf16 v[32:35], v[206:209], v[222:225], v[32:35]
	v_mfma_f32_16x16x32_bf16 v[24:27], v[158:161], v[230:233], v[24:27]
	v_mfma_f32_16x16x32_bf16 v[16:19], v[206:209], v[230:233], v[16:19]
	v_mfma_f32_16x16x32_bf16 v[8:11], v[158:161], v[238:241], v[8:11]
	v_mfma_f32_16x16x32_bf16 v[4:7], v[206:209], v[238:241], v[4:7]
	v_mfma_f32_16x16x32_bf16 v[56:59], v[174:177], v[218:221], v[56:59]
	v_mfma_f32_16x16x32_bf16 v[48:51], v[210:213], v[218:221], v[48:51]
	v_mfma_f32_16x16x32_bf16 v[40:43], v[174:177], v[226:229], v[40:43]
	v_mfma_f32_16x16x32_bf16 v[32:35], v[210:213], v[226:229], v[32:35]
	v_mfma_f32_16x16x32_bf16 v[24:27], v[174:177], v[234:237], v[24:27]
	v_mfma_f32_16x16x32_bf16 v[16:19], v[210:213], v[234:237], v[16:19]
	v_mfma_f32_16x16x32_bf16 v[8:11], v[174:177], v[242:245], v[8:11]
	v_mfma_f32_16x16x32_bf16 v[4:7], v[210:213], v[242:245], v[4:7]
	s_setprio 3
	s_barrier
	s_add_i32 s63, s63, 2
	s_add_u32 s40, s40, 0x100
	s_addc_u32 s41, s41, 0
	s_add_u32 s35, s35, 0x100
	s_addc_u32 s62, s62, 0
	s_cmp_gt_u32 s63, 29
	s_cbranch_scc0 .LBB0_674
	s_and_b64 vcc, exec, s[30:31]
	s_cbranch_vccz .LBB0_677
	s_barrier

; #define PG8_STAGE(bufoff, gbase, voff) do { _Pragma("unroll") for (int _i = 0; _i < 2; ++_i) \
;         __builtin_amdgcn_global_load_lds((const unsigned*)((const char*)(gbase) + (voff)[_i]), (PG8_LAS unsigned*)(lds + (bufoff) + ldsw + _i * 8192), 16, 0, 0); } while (0)
; #define PG8_LDA(dst, b, h) do { _Pragma("unroll") for (int m = 0; m < 4; ++m) _Pragma("unroll") for (int k = 0; k < 2; ++k) dst[m][k] = *(const PG8_LAS bf16x8*)(lds + PG8_SA(b, h) + aoff + m * 2048 + k * 1024); } while (0)
; #define PG8_LDB(dst, b, h) do { _Pragma("unroll") for (int n = 0; n < 2; ++n) _Pragma("unroll") for (int k = 0; k < 2; ++k) dst[n][k] = *(const PG8_LAS bf16x8*)(lds + PG8_SB(b, h) + boff + n * 2048 + k * 1024); } while (0)
; #define PG8_MMA(ai, bj, At, Bt) do { __builtin_amdgcn_s_setprio(1); _Pragma("unroll") for (int m = 0; m < 4; ++m) _Pragma("unroll") for (int n = 0; n < 2; ++n) _Pragma("unroll") for (int k = 0; k < 2; ++k) \
;         acc[ai][bj][m][n] = __builtin_amdgcn_mfma_f32_16x16x32_bf16(Bt[n][k], At[m][k], acc[ai][bj][m][n], 0, 0, 0); __builtin_amdgcn_s_setprio(0); } while (0)
; #define PG8_WAIT_V(n) asm volatile("s_waitcnt vmcnt(" #n ")" ::: "memory")
; #define PG8_WAIT_L(n) asm volatile("s_waitcnt lgkmcnt(" #n ")" ::: "memory")
; #define PG8_BAR __builtin_amdgcn_s_barrier()
; #define PG8_SCHED __builtin_amdgcn_sched_barrier(0)
; template <class Epi, class Sched, bool ALIGN_EPI = false, bool SP2 = false>
; __device__ __forceinline__ void gemm_phase(PG8_LAS unsigned char* lds, const Gemm g, const Sched& S, const Epi& E) {
;     ...
;             PG8_LDB(B0, 0, 0); PG8_LDB(B1, 0, 1); PG8_SCHED; PG8_LDA(At, 0, 0); PG8_STAGE(PG8_SA(1, 1), a1 + hstep, voffA);
;             PG8_WAIT_V(8); PG8_WAIT_L(0); PG8_BAR; PG8_MMA(0, 0, At, B0); PG8_MMA(0, 1, At, B1); PG8_BAR; PG8_SCHED;
;             PG8_LDA(At, 0, 1); PG8_STAGE(PG8_SB(0, 0), b2, voffB); PG8_STAGE(PG8_SB(0, 1), b2 + hstep, voffB); PG8_STAGE(PG8_SA(0, 0), a2, voffA);
;             PG8_WAIT_V(8); PG8_WAIT_L(0); PG8_BAR; PG8_MMA(1, 0, At, B0); PG8_MMA(1, 1, At, B1); PG8_BAR; PG8_SCHED;
.LBB0_2096:
	s_add_u32 s27, s40, 0xfffc0080
	s_addc_u32 s29, s41, -1
	s_add_i32 s31, 0, 0x10000
	s_cmp_eq_u32 s26, 12
	s_cselect_b32 s45, s1, s29
	s_cselect_b32 s44, s0, s27
	s_cselect_b32 s43, s35, s13
	s_cselect_b32 s42, s34, s11
	s_add_i32 s27, 0, 0x14000
	ds_read_b128 v[134:137], v175
	ds_read_b128 v[138:141], v175 offset:1024
	ds_read_b128 v[154:157], v175 offset:2048
	ds_read_b128 v[158:161], v175 offset:3072
	ds_read_b128 v[178:181], v175 offset:16384
	ds_read_b128 v[204:207], v175 offset:17408
	ds_read_b128 v[208:211], v175 offset:18432
	ds_read_b128 v[212:215], v175 offset:19456
	s_add_i32 m0, s55, 0xc000
	ds_read_b128 v[216:219], v177
	ds_read_b128 v[220:223], v177 offset:1024
	ds_read_b128 v[224:227], v177 offset:2048
	ds_read_b128 v[228:231], v177 offset:3072
	ds_read_b128 v[232:235], v177 offset:4096
	ds_read_b128 v[236:239], v177 offset:5120
	ds_read_b128 v[240:243], v177 offset:6144
	ds_read_b128 v[244:247], v177 offset:7168
	global_load_lds_dwordx4 v150, s[40:41]
	s_add_i32 m0, s55, 0xe000
	s_nop 0
	global_load_lds_dwordx4 v152, s[40:41]
	s_waitcnt vmcnt(8) lgkmcnt(0)
	s_setprio 0
	s_barrier
	v_mfma_f32_16x16x32_bf16 v[130:133], v[134:137], v[216:219], v[130:133]
	v_mfma_f32_16x16x32_bf16 v[126:129], v[154:157], v[216:219], v[126:129]
	v_mfma_f32_16x16x32_bf16 v[122:125], v[134:137], v[224:227], v[122:125]
	v_mfma_f32_16x16x32_bf16 v[118:121], v[154:157], v[224:227], v[118:121]
	v_mfma_f32_16x16x32_bf16 v[114:117], v[134:137], v[232:235], v[114:117]
	v_mfma_f32_16x16x32_bf16 v[110:113], v[154:157], v[232:235], v[110:113]
	v_mfma_f32_16x16x32_bf16 v[106:109], v[134:137], v[240:243], v[106:109]
	v_mfma_f32_16x16x32_bf16 v[102:105], v[154:157], v[240:243], v[102:105]
	v_mfma_f32_16x16x32_bf16 v[130:133], v[138:141], v[220:223], v[130:133]
	v_mfma_f32_16x16x32_bf16 v[126:129], v[158:161], v[220:223], v[126:129]
	v_mfma_f32_16x16x32_bf16 v[122:125], v[138:141], v[228:231], v[122:125]
	v_mfma_f32_16x16x32_bf16 v[118:121], v[158:161], v[228:231], v[118:121]
	v_mfma_f32_16x16x32_bf16 v[114:117], v[138:141], v[236:239], v[114:117]
	v_mfma_f32_16x16x32_bf16 v[110:113], v[158:161], v[236:239], v[110:113]
	v_mfma_f32_16x16x32_bf16 v[106:109], v[138:141], v[244:247], v[106:109]
	v_mfma_f32_16x16x32_bf16 v[102:105], v[158:161], v[244:247], v[102:105]
	v_mfma_f32_16x16x32_bf16 v[98:101], v[178:181], v[216:219], v[98:101]
	v_mfma_f32_16x16x32_bf16 v[94:97], v[208:211], v[216:219], v[94:97]
	v_mfma_f32_16x16x32_bf16 v[90:93], v[178:181], v[224:227], v[90:93]
	v_mfma_f32_16x16x32_bf16 v[86:89], v[208:211], v[224:227], v[86:89]
	v_mfma_f32_16x16x32_bf16 v[82:85], v[178:181], v[232:235], v[82:85]
	v_mfma_f32_16x16x32_bf16 v[78:81], v[208:211], v[232:235], v[78:81]
	v_mfma_f32_16x16x32_bf16 v[74:77], v[178:181], v[240:243], v[74:77]
	v_mfma_f32_16x16x32_bf16 v[70:73], v[208:211], v[240:243], v[70:73]
	v_mfma_f32_16x16x32_bf16 v[98:101], v[204:207], v[220:223], v[98:101]
	v_mfma_f32_16x16x32_bf16 v[94:97], v[212:215], v[220:223], v[94:97]
	v_mfma_f32_16x16x32_bf16 v[90:93], v[204:207], v[228:231], v[90:93]
	v_mfma_f32_16x16x32_bf16 v[86:89], v[212:215], v[228:231], v[86:89]
	v_mfma_f32_16x16x32_bf16 v[82:85], v[204:207], v[236:239], v[82:85]
	v_mfma_f32_16x16x32_bf16 v[78:81], v[212:215], v[236:239], v[78:81]
	v_mfma_f32_16x16x32_bf16 v[74:77], v[204:207], v[244:247], v[74:77]
	v_mfma_f32_16x16x32_bf16 v[70:73], v[212:215], v[244:247], v[70:73]
	s_setprio 3
	s_barrier
	s_add_i32 s29, s31, s54
	s_mov_b32 m0, s29
	ds_read_b128 v[216:219], v177 offset:16384
	ds_read_b128 v[220:223], v177 offset:17408
	ds_read_b128 v[224:227], v177 offset:18432
	ds_read_b128 v[228:231], v177 offset:19456
	ds_read_b128 v[232:235], v177 offset:20480
	ds_read_b128 v[236:239], v177 offset:21504
	ds_read_b128 v[240:243], v177 offset:22528
	ds_read_b128 v[244:247], v177 offset:23552
	global_load_lds_dwordx4 v144, s[42:43]
	s_add_i32 m0, s29, 0x2000
	s_add_u32 s64, s42, 0x40000
	s_addc_u32 s65, s43, 0
	s_add_i32 s27, s27, s54
	global_load_lds_dwordx4 v148, s[42:43]
	s_mov_b32 m0, s27
	s_nop 0
	global_load_lds_dwordx4 v144, s[64:65]
	s_add_i32 m0, s27, 0x2000
	s_nop 0
	global_load_lds_dwordx4 v148, s[64:65]
	s_mov_b32 m0, s55
	s_nop 0
	global_load_lds_dwordx4 v142, s[44:45]
	s_mov_b32 m0, s56
	s_nop 0
	global_load_lds_dwordx4 v146, s[44:45]
	s_waitcnt vmcnt(8) lgkmcnt(0)
	s_setprio 0
	s_barrier
	v_mfma_f32_16x16x32_bf16 v[66:69], v[134:137], v[216:219], v[66:69]
	v_mfma_f32_16x16x32_bf16 v[62:65], v[154:157], v[216:219], v[62:65]
	v_mfma_f32_16x16x32_bf16 v[58:61], v[134:137], v[224:227], v[58:61]
	v_mfma_f32_16x16x32_bf16 v[54:57], v[154:157], v[224:227], v[54:57]
	v_mfma_f32_16x16x32_bf16 v[50:53], v[134:137], v[232:235], v[50:53]
	v_mfma_f32_16x16x32_bf16 v[46:49], v[154:157], v[232:235], v[46:49]
	v_mfma_f32_16x16x32_bf16 v[42:45], v[134:137], v[240:243], v[42:45]
	v_mfma_f32_16x16x32_bf16 v[38:41], v[154:157], v[240:243], v[38:41]
	v_mfma_f32_16x16x32_bf16 v[66:69], v[138:141], v[220:223], v[66:69]
	v_mfma_f32_16x16x32_bf16 v[62:65], v[158:161], v[220:223], v[62:65]
	v_mfma_f32_16x16x32_bf16 v[58:61], v[138:141], v[228:231], v[58:61]
	v_mfma_f32_16x16x32_bf16 v[54:57], v[158:161], v[228:231], v[54:57]
	v_mfma_f32_16x16x32_bf16 v[50:53], v[138:141], v[236:239], v[50:53]
	v_mfma_f32_16x16x32_bf16 v[46:49], v[158:161], v[236:239], v[46:49]
	v_mfma_f32_16x16x32_bf16 v[42:45], v[138:141], v[244:247], v[42:45]
	v_mfma_f32_16x16x32_bf16 v[38:41], v[158:161], v[244:247], v[38:41]
	v_mfma_f32_16x16x32_bf16 v[34:37], v[178:181], v[216:219], v[34:37]
	v_mfma_f32_16x16x32_bf16 v[30:33], v[208:211], v[216:219], v[30:33]
	v_mfma_f32_16x16x32_bf16 v[26:29], v[178:181], v[224:227], v[26:29]
	v_mfma_f32_16x16x32_bf16 v[22:25], v[208:211], v[224:227], v[22:25]
	v_mfma_f32_16x16x32_bf16 v[18:21], v[178:181], v[232:235], v[18:21]
	v_mfma_f32_16x16x32_bf16 v[14:17], v[208:211], v[232:235], v[14:17]
	v_mfma_f32_16x16x32_bf16 v[10:13], v[178:181], v[240:243], v[10:13]
	v_mfma_f32_16x16x32_bf16 v[4:7], v[208:211], v[240:243], v[6:9]
	v_mfma_f32_16x16x32_bf16 v[34:37], v[204:207], v[220:223], v[34:37]
	v_mfma_f32_16x16x32_bf16 v[30:33], v[212:215], v[220:223], v[30:33]
	v_mfma_f32_16x16x32_bf16 v[26:29], v[204:207], v[228:231], v[26:29]
	v_mfma_f32_16x16x32_bf16 v[22:25], v[212:215], v[228:231], v[22:25]
	v_mfma_f32_16x16x32_bf16 v[18:21], v[204:207], v[236:239], v[18:21]
	v_mfma_f32_16x16x32_bf16 v[14:17], v[212:215], v[236:239], v[14:17]
	v_mfma_f32_16x16x32_bf16 v[10:13], v[204:207], v[244:247], v[10:13]
	v_mfma_f32_16x16x32_bf16 v[4:7], v[212:215], v[244:247], v[4:7]
	s_setprio 3
	s_barrier
; #define PG8_STAGE(bufoff, gbase, voff) do { _Pragma("unroll") for (int _i = 0; _i < 2; ++_i) \
;         __builtin_amdgcn_global_load_lds((const unsigned*)((const char*)(gbase) + (voff)[_i]), (PG8_LAS unsigned*)(lds + (bufoff) + ldsw + _i * 8192), 16, 0, 0); } while (0)
; #define PG8_LDA(dst, b, h) do { _Pragma("unroll") for (int m = 0; m < 4; ++m) _Pragma("unroll") for (int k = 0; k < 2; ++k) dst[m][k] = *(const PG8_LAS bf16x8*)(lds + PG8_SA(b, h) + aoff + m * 2048 + k * 1024); } while (0)
; #define PG8_LDB(dst, b, h) do { _Pragma("unroll") for (int n = 0; n < 2; ++n) _Pragma("unroll") for (int k = 0; k < 2; ++k) dst[n][k] = *(const PG8_LAS bf16x8*)(lds + PG8_SB(b, h) + boff + n * 2048 + k * 1024); } while (0)
; #define PG8_MMA(ai, bj, At, Bt) do { __builtin_amdgcn_s_setprio(1); _Pragma("unroll") for (int m = 0; m < 4; ++m) _Pragma("unroll") for (int n = 0; n < 2; ++n) _Pragma("unroll") for (int k = 0; k < 2; ++k) \
;         acc[ai][bj][m][n] = __builtin_amdgcn_mfma_f32_16x16x32_bf16(Bt[n][k], At[m][k], acc[ai][bj][m][n], 0, 0, 0); __builtin_amdgcn_s_setprio(0); } while (0)
; #define PG8_WAIT_V(n) asm volatile("s_waitcnt vmcnt(" #n ")" ::: "memory")
; #define PG8_WAIT_L(n) asm volatile("s_waitcnt lgkmcnt(" #n ")" ::: "memory")
; #define PG8_BAR __builtin_amdgcn_s_barrier()
; #define PG8_SCHED __builtin_amdgcn_sched_barrier(0)
; template <class Epi, class Sched, bool ALIGN_EPI = false, bool SP2 = false>
; __device__ __forceinline__ void gemm_phase(PG8_LAS unsigned char* lds, const Gemm g, const Sched& S, const Epi& E) {
;     ...
;             PG8_LDB(B0, 1, 0); PG8_LDB(B1, 1, 1); PG8_SCHED; PG8_LDA(At, 1, 0); PG8_STAGE(PG8_SA(0, 1), a2 + hstep, voffA);
;             PG8_WAIT_V(8); PG8_WAIT_L(0); PG8_BAR; PG8_MMA(0, 0, At, B0); PG8_MMA(0, 1, At, B1); PG8_BAR; PG8_SCHED;
;             PG8_LDA(At, 1, 1); PG8_STAGE(PG8_SB(1, 0), b3, voffB); PG8_STAGE(PG8_SB(1, 1), b3 + hstep, voffB); PG8_STAGE(PG8_SA(1, 0), a3, voffA);
;             PG8_WAIT_V(8); PG8_WAIT_L(0); PG8_BAR; PG8_MMA(1, 0, At, B0); PG8_MMA(1, 1, At, B1); PG8_BAR; PG8_SCHED;
	s_add_i32 s27, 0, 0x18000
	s_add_i32 s29, 0, 0x1c000
	ds_read_b128 v[134:137], v175 offset:32768
	ds_read_b128 v[138:141], v175 offset:33792
	ds_read_b128 v[154:157], v175 offset:34816
	ds_read_b128 v[158:161], v175 offset:35840
	ds_read_b128 v[178:181], v175 offset:49152
	ds_read_b128 v[204:207], v175 offset:50176
	ds_read_b128 v[208:211], v175 offset:51200
	ds_read_b128 v[212:215], v175 offset:52224
	s_add_u32 s100, s44, 0x80
	s_addc_u32 s101, s45, 0
	s_add_u32 s44, s44, 0x40000
	s_addc_u32 s45, s45, 0
	s_mov_b32 m0, s57
	ds_read_b128 v[216:219], v177 offset:32768
	ds_read_b128 v[220:223], v177 offset:33792
	ds_read_b128 v[224:227], v177 offset:34816
	ds_read_b128 v[228:231], v177 offset:35840
	ds_read_b128 v[232:235], v177 offset:36864
	ds_read_b128 v[236:239], v177 offset:37888
	ds_read_b128 v[240:243], v177 offset:38912
	ds_read_b128 v[244:247], v177 offset:39936
	global_load_lds_dwordx4 v142, s[44:45]
	s_mov_b32 m0, s58
	s_nop 0
	global_load_lds_dwordx4 v146, s[44:45]
	s_waitcnt vmcnt(8) lgkmcnt(0)
	s_setprio 0
	s_barrier
	v_mfma_f32_16x16x32_bf16 v[130:133], v[134:137], v[216:219], v[130:133]
	v_mfma_f32_16x16x32_bf16 v[126:129], v[154:157], v[216:219], v[126:129]
	v_mfma_f32_16x16x32_bf16 v[122:125], v[134:137], v[224:227], v[122:125]
	v_mfma_f32_16x16x32_bf16 v[118:121], v[154:157], v[224:227], v[118:121]
	v_mfma_f32_16x16x32_bf16 v[114:117], v[134:137], v[232:235], v[114:117]
	v_mfma_f32_16x16x32_bf16 v[110:113], v[154:157], v[232:235], v[110:113]
	v_mfma_f32_16x16x32_bf16 v[106:109], v[134:137], v[240:243], v[106:109]
	v_mfma_f32_16x16x32_bf16 v[102:105], v[154:157], v[240:243], v[102:105]
	v_mfma_f32_16x16x32_bf16 v[130:133], v[138:141], v[220:223], v[130:133]
	v_mfma_f32_16x16x32_bf16 v[126:129], v[158:161], v[220:223], v[126:129]
	v_mfma_f32_16x16x32_bf16 v[122:125], v[138:141], v[228:231], v[122:125]
	v_mfma_f32_16x16x32_bf16 v[118:121], v[158:161], v[228:231], v[118:121]
	v_mfma_f32_16x16x32_bf16 v[114:117], v[138:141], v[236:239], v[114:117]
	v_mfma_f32_16x16x32_bf16 v[110:113], v[158:161], v[236:239], v[110:113]
	v_mfma_f32_16x16x32_bf16 v[106:109], v[138:141], v[244:247], v[106:109]
	v_mfma_f32_16x16x32_bf16 v[102:105], v[158:161], v[244:247], v[102:105]
	v_mfma_f32_16x16x32_bf16 v[98:101], v[178:181], v[216:219], v[98:101]
	v_mfma_f32_16x16x32_bf16 v[94:97], v[208:211], v[216:219], v[94:97]
	v_mfma_f32_16x16x32_bf16 v[90:93], v[178:181], v[224:227], v[90:93]
	v_mfma_f32_16x16x32_bf16 v[86:89], v[208:211], v[224:227], v[86:89]
	v_mfma_f32_16x16x32_bf16 v[82:85], v[178:181], v[232:235], v[82:85]
	v_mfma_f32_16x16x32_bf16 v[78:81], v[208:211], v[232:235], v[78:81]
	v_mfma_f32_16x16x32_bf16 v[74:77], v[178:181], v[240:243], v[74:77]
	v_mfma_f32_16x16x32_bf16 v[70:73], v[208:211], v[240:243], v[70:73]
	v_mfma_f32_16x16x32_bf16 v[98:101], v[204:207], v[220:223], v[98:101]
	v_mfma_f32_16x16x32_bf16 v[94:97], v[212:215], v[220:223], v[94:97]
	v_mfma_f32_16x16x32_bf16 v[90:93], v[204:207], v[228:231], v[90:93]
	v_mfma_f32_16x16x32_bf16 v[86:89], v[212:215], v[228:231], v[86:89]
	v_mfma_f32_16x16x32_bf16 v[82:85], v[204:207], v[236:239], v[82:85]
	v_mfma_f32_16x16x32_bf16 v[78:81], v[212:215], v[236:239], v[78:81]
	v_mfma_f32_16x16x32_bf16 v[74:77], v[204:207], v[244:247], v[74:77]
	v_mfma_f32_16x16x32_bf16 v[70:73], v[212:215], v[244:247], v[70:73]
	s_setprio 3
	s_barrier
	s_add_i32 s27, s27, s54
	s_add_i32 m0, s27, 0xffffff80
	ds_read_b128 v[216:219], v177 offset:49152
	ds_read_b128 v[220:223], v177 offset:50176
	ds_read_b128 v[224:227], v177 offset:51200
	ds_read_b128 v[228:231], v177 offset:52224
	ds_read_b128 v[232:235], v177 offset:53248
	ds_read_b128 v[236:239], v177 offset:54272
	ds_read_b128 v[240:243], v177 offset:55296
	ds_read_b128 v[244:247], v177 offset:56320
	global_load_lds_dwordx4 v144, s[42:43] offset:128
	s_add_i32 m0, s27, 0x1f80
	s_add_i32 s27, s29, s54
	global_load_lds_dwordx4 v148, s[42:43] offset:128
	s_add_u32 s42, s42, 0x40080
	s_addc_u32 s43, s43, 0
	s_mov_b32 m0, s27
	s_nop 0
	global_load_lds_dwordx4 v144, s[42:43]
	s_add_i32 m0, s27, 0x2000
	s_nop 0
	global_load_lds_dwordx4 v148, s[42:43]
	s_mov_b32 m0, s61
	s_nop 0
	global_load_lds_dwordx4 v142, s[100:101]
	s_mov_b32 m0, s62
	s_nop 0
	global_load_lds_dwordx4 v146, s[100:101]
	s_nop 0
	s_waitcnt vmcnt(8) lgkmcnt(0)
	s_setprio 0
	s_barrier
	v_mfma_f32_16x16x32_bf16 v[66:69], v[134:137], v[216:219], v[66:69]
	v_mfma_f32_16x16x32_bf16 v[62:65], v[154:157], v[216:219], v[62:65]
	v_mfma_f32_16x16x32_bf16 v[58:61], v[134:137], v[224:227], v[58:61]
	v_mfma_f32_16x16x32_bf16 v[54:57], v[154:157], v[224:227], v[54:57]
	v_mfma_f32_16x16x32_bf16 v[50:53], v[134:137], v[232:235], v[50:53]
	v_mfma_f32_16x16x32_bf16 v[46:49], v[154:157], v[232:235], v[46:49]
	v_mfma_f32_16x16x32_bf16 v[42:45], v[134:137], v[240:243], v[42:45]
	v_mfma_f32_16x16x32_bf16 v[38:41], v[154:157], v[240:243], v[38:41]
	v_mfma_f32_16x16x32_bf16 v[66:69], v[138:141], v[220:223], v[66:69]
	v_mfma_f32_16x16x32_bf16 v[62:65], v[158:161], v[220:223], v[62:65]
	v_mfma_f32_16x16x32_bf16 v[58:61], v[138:141], v[228:231], v[58:61]
	v_mfma_f32_16x16x32_bf16 v[54:57], v[158:161], v[228:231], v[54:57]
	v_mfma_f32_16x16x32_bf16 v[50:53], v[138:141], v[236:239], v[50:53]
	v_mfma_f32_16x16x32_bf16 v[46:49], v[158:161], v[236:239], v[46:49]
	v_mfma_f32_16x16x32_bf16 v[42:45], v[138:141], v[244:247], v[42:45]
	v_mfma_f32_16x16x32_bf16 v[38:41], v[158:161], v[244:247], v[38:41]
	v_mfma_f32_16x16x32_bf16 v[34:37], v[178:181], v[216:219], v[34:37]
	v_mfma_f32_16x16x32_bf16 v[30:33], v[208:211], v[216:219], v[30:33]
	v_mfma_f32_16x16x32_bf16 v[26:29], v[178:181], v[224:227], v[26:29]
	v_mfma_f32_16x16x32_bf16 v[22:25], v[208:211], v[224:227], v[22:25]
	v_mfma_f32_16x16x32_bf16 v[18:21], v[178:181], v[232:235], v[18:21]
	v_mfma_f32_16x16x32_bf16 v[14:17], v[208:211], v[232:235], v[14:17]
	v_mfma_f32_16x16x32_bf16 v[8:11], v[178:181], v[240:243], v[10:13]
	v_mfma_f32_16x16x32_bf16 v[4:7], v[208:211], v[240:243], v[4:7]
	v_mfma_f32_16x16x32_bf16 v[34:37], v[204:207], v[220:223], v[34:37]
	v_mfma_f32_16x16x32_bf16 v[30:33], v[212:215], v[220:223], v[30:33]
	v_mfma_f32_16x16x32_bf16 v[26:29], v[204:207], v[228:231], v[26:29]
	v_mfma_f32_16x16x32_bf16 v[22:25], v[212:215], v[228:231], v[22:25]
	v_mfma_f32_16x16x32_bf16 v[18:21], v[204:207], v[236:239], v[18:21]
	v_mfma_f32_16x16x32_bf16 v[14:17], v[212:215], v[236:239], v[14:17]
	v_mfma_f32_16x16x32_bf16 v[10:13], v[204:207], v[244:247], v[8:11]
	v_mfma_f32_16x16x32_bf16 v[6:9], v[212:215], v[244:247], v[4:7]
	s_setprio 3
	s_barrier
	s_add_i32 s26, s26, 2
	s_add_u32 s40, s40, 0x100
	s_addc_u32 s41, s41, 0
	s_add_u32 s11, s11, 0x100
	s_addc_u32 s13, s13, 0
	s_cmp_gt_u32 s26, 13
	s_cbranch_scc0 .LBB0_2096
	s_and_b64 vcc, exec, s[8:9]
	s_cbranch_vccz .LBB0_2099
	s_barrier

; #define PG8_STAGE(bufoff, gbase, voff) do { _Pragma("unroll") for (int _i = 0; _i < 2; ++_i) \
;         __builtin_amdgcn_global_load_lds((const unsigned*)((const char*)(gbase) + (voff)[_i]), (PG8_LAS unsigned*)(lds + (bufoff) + ldsw + _i * 8192), 16, 0, 0); } while (0)
; #define PG8_LDA(dst, b, h) do { _Pragma("unroll") for (int m = 0; m < 4; ++m) _Pragma("unroll") for (int k = 0; k < 2; ++k) dst[m][k] = *(const PG8_LAS bf16x8*)(lds + PG8_SA(b, h) + aoff + m * 2048 + k * 1024); } while (0)
; #define PG8_LDB(dst, b, h) do { _Pragma("unroll") for (int n = 0; n < 2; ++n) _Pragma("unroll") for (int k = 0; k < 2; ++k) dst[n][k] = *(const PG8_LAS bf16x8*)(lds + PG8_SB(b, h) + boff + n * 2048 + k * 1024); } while (0)
; #define PG8_MMA(ai, bj, At, Bt) do { __builtin_amdgcn_s_setprio(1); _Pragma("unroll") for (int m = 0; m < 4; ++m) _Pragma("unroll") for (int n = 0; n < 2; ++n) _Pragma("unroll") for (int k = 0; k < 2; ++k) \
;         acc[ai][bj][m][n] = __builtin_amdgcn_mfma_f32_16x16x32_bf16(Bt[n][k], At[m][k], acc[ai][bj][m][n], 0, 0, 0); __builtin_amdgcn_s_setprio(0); } while (0)
; #define PG8_WAIT_V(n) asm volatile("s_waitcnt vmcnt(" #n ")" ::: "memory")
; #define PG8_WAIT_L(n) asm volatile("s_waitcnt lgkmcnt(" #n ")" ::: "memory")
; #define PG8_BAR __builtin_amdgcn_s_barrier()
; #define PG8_SCHED __builtin_amdgcn_sched_barrier(0)
; template <class Epi, class Sched, bool ALIGN_EPI = false, bool SP2 = false>
; __device__ __forceinline__ void gemm_phase(PG8_LAS unsigned char* lds, const Gemm g, const Sched& S, const Epi& E) {
;     ...
;             PG8_LDB(B0, 0, 0); PG8_LDB(B1, 0, 1); PG8_SCHED; PG8_LDA(At, 0, 0); PG8_STAGE(PG8_SA(1, 1), a1 + hstep, voffA);
;             PG8_WAIT_V(8); PG8_WAIT_L(0); PG8_BAR; PG8_MMA(0, 0, At, B0); PG8_MMA(0, 1, At, B1); PG8_BAR; PG8_SCHED;
;             PG8_LDA(At, 0, 1); PG8_STAGE(PG8_SB(0, 0), b2, voffB); PG8_STAGE(PG8_SB(0, 1), b2 + hstep, voffB); PG8_STAGE(PG8_SA(0, 0), a2, voffA);
;             PG8_WAIT_V(8); PG8_WAIT_L(0); PG8_BAR; PG8_MMA(1, 0, At, B0); PG8_MMA(1, 1, At, B1); PG8_BAR; PG8_SCHED;
.LBB0_2185:
	s_add_u32 s42, s40, 0x100
	s_addc_u32 s43, s41, 0
	s_add_i32 s37, 0, 0x10000
	s_cmp_eq_u32 s31, 28
	s_cselect_b32 s47, s5, s43
	s_cselect_b32 s46, s4, s42
	s_cselect_b32 s45, s35, s29
	s_cselect_b32 s44, s34, s2
	s_add_i32 s39, 0, 0x14000
	ds_read_b128 v[142:145], v243
	ds_read_b128 v[146:149], v243 offset:1024
	ds_read_b128 v[150:153], v243 offset:2048
	ds_read_b128 v[154:157], v243 offset:3072
	ds_read_b128 v[158:161], v243 offset:16384
	ds_read_b128 v[174:177], v243 offset:17408
	ds_read_b128 v[180:183], v243 offset:18432
	ds_read_b128 v[204:207], v243 offset:19456
	v_lshl_add_u64 v[162:163], s[40:41], 0, v[138:139]
	s_add_i32 m0, s55, 0xc000
	ds_read_b128 v[208:211], v179
	ds_read_b128 v[212:215], v179 offset:1024
	ds_read_b128 v[216:219], v179 offset:2048
	ds_read_b128 v[220:223], v179 offset:3072
	ds_read_b128 v[224:227], v179 offset:4096
	ds_read_b128 v[228:231], v179 offset:5120
	ds_read_b128 v[232:235], v179 offset:6144
	ds_read_b128 v[236:239], v179 offset:7168
	global_load_lds_dwordx4 v[162:163], off
	v_lshl_add_u64 v[162:163], s[40:41], 0, v[140:141]
	s_add_i32 m0, s55, 0xe000
	s_nop 0
	global_load_lds_dwordx4 v[162:163], off
	s_waitcnt vmcnt(8) lgkmcnt(0)
	s_setprio 0
	s_barrier
	v_mfma_f32_16x16x32_bf16 v[128:131], v[142:145], v[208:211], v[128:131]
	v_mfma_f32_16x16x32_bf16 v[124:127], v[150:153], v[208:211], v[124:127]
	v_mfma_f32_16x16x32_bf16 v[112:115], v[142:145], v[216:219], v[112:115]
	v_mfma_f32_16x16x32_bf16 v[108:111], v[150:153], v[216:219], v[108:111]
	v_mfma_f32_16x16x32_bf16 v[96:99], v[142:145], v[224:227], v[96:99]
	v_mfma_f32_16x16x32_bf16 v[92:95], v[150:153], v[224:227], v[92:95]
	v_mfma_f32_16x16x32_bf16 v[80:83], v[142:145], v[232:235], v[80:83]
	v_mfma_f32_16x16x32_bf16 v[76:79], v[150:153], v[232:235], v[76:79]
	v_mfma_f32_16x16x32_bf16 v[128:131], v[146:149], v[212:215], v[128:131]
	v_mfma_f32_16x16x32_bf16 v[124:127], v[154:157], v[212:215], v[124:127]
	v_mfma_f32_16x16x32_bf16 v[112:115], v[146:149], v[220:223], v[112:115]
	v_mfma_f32_16x16x32_bf16 v[108:111], v[154:157], v[220:223], v[108:111]
	v_mfma_f32_16x16x32_bf16 v[96:99], v[146:149], v[228:231], v[96:99]
	v_mfma_f32_16x16x32_bf16 v[92:95], v[154:157], v[228:231], v[92:95]
	v_mfma_f32_16x16x32_bf16 v[80:83], v[146:149], v[236:239], v[80:83]
	v_mfma_f32_16x16x32_bf16 v[76:79], v[154:157], v[236:239], v[76:79]
	v_mfma_f32_16x16x32_bf16 v[120:123], v[158:161], v[208:211], v[120:123]
	v_mfma_f32_16x16x32_bf16 v[116:119], v[180:183], v[208:211], v[116:119]
	v_mfma_f32_16x16x32_bf16 v[104:107], v[158:161], v[216:219], v[104:107]
	v_mfma_f32_16x16x32_bf16 v[100:103], v[180:183], v[216:219], v[100:103]
	v_mfma_f32_16x16x32_bf16 v[88:91], v[158:161], v[224:227], v[88:91]
	v_mfma_f32_16x16x32_bf16 v[84:87], v[180:183], v[224:227], v[84:87]
	v_mfma_f32_16x16x32_bf16 v[72:75], v[158:161], v[232:235], v[72:75]
	v_mfma_f32_16x16x32_bf16 v[68:71], v[180:183], v[232:235], v[68:71]
	v_mfma_f32_16x16x32_bf16 v[120:123], v[174:177], v[212:215], v[120:123]
	v_mfma_f32_16x16x32_bf16 v[116:119], v[204:207], v[212:215], v[116:119]
	v_mfma_f32_16x16x32_bf16 v[104:107], v[174:177], v[220:223], v[104:107]
	v_mfma_f32_16x16x32_bf16 v[100:103], v[204:207], v[220:223], v[100:103]
	v_mfma_f32_16x16x32_bf16 v[88:91], v[174:177], v[228:231], v[88:91]
	v_mfma_f32_16x16x32_bf16 v[84:87], v[204:207], v[228:231], v[84:87]
	v_mfma_f32_16x16x32_bf16 v[72:75], v[174:177], v[236:239], v[72:75]
	v_mfma_f32_16x16x32_bf16 v[68:71], v[204:207], v[236:239], v[68:71]
	s_setprio 3
	s_barrier
	s_add_i32 s37, s37, s54
	s_mov_b32 m0, s37
	ds_read_b128 v[208:211], v179 offset:16384
	ds_read_b128 v[212:215], v179 offset:17408
	ds_read_b128 v[216:219], v179 offset:18432
	ds_read_b128 v[220:223], v179 offset:19456
	ds_read_b128 v[224:227], v179 offset:20480
	ds_read_b128 v[228:231], v179 offset:21504
	ds_read_b128 v[232:235], v179 offset:22528
	ds_read_b128 v[236:239], v179 offset:23552
	global_load_lds_dwordx4 v2, s[44:45]
	s_add_i32 m0, s37, 0x2000
	s_add_u32 s40, s44, 0x80000
	s_addc_u32 s41, s45, 0
	s_add_i32 s37, s39, s54
	global_load_lds_dwordx4 v132, s[44:45]
	s_mov_b32 m0, s37
	s_nop 0
	global_load_lds_dwordx4 v2, s[40:41]
	s_add_i32 m0, s37, 0x2000
	s_nop 0
	global_load_lds_dwordx4 v132, s[40:41]
	s_mov_b32 m0, s55
	s_nop 0
	global_load_lds_dwordx4 v2, s[46:47]
	s_mov_b32 m0, s56
	s_nop 0
	global_load_lds_dwordx4 v132, s[46:47]
	s_waitcnt vmcnt(8) lgkmcnt(0)
	s_setprio 0
	s_barrier
	v_mfma_f32_16x16x32_bf16 v[64:67], v[142:145], v[208:211], v[64:67]
	v_mfma_f32_16x16x32_bf16 v[60:63], v[150:153], v[208:211], v[60:63]
	v_mfma_f32_16x16x32_bf16 v[48:51], v[142:145], v[216:219], v[48:51]
	v_mfma_f32_16x16x32_bf16 v[44:47], v[150:153], v[216:219], v[44:47]
	v_mfma_f32_16x16x32_bf16 v[32:35], v[142:145], v[224:227], v[32:35]
	v_mfma_f32_16x16x32_bf16 v[28:31], v[150:153], v[224:227], v[28:31]
	v_mfma_f32_16x16x32_bf16 v[16:19], v[142:145], v[232:235], v[16:19]
	v_mfma_f32_16x16x32_bf16 v[12:15], v[150:153], v[232:235], v[12:15]
	v_mfma_f32_16x16x32_bf16 v[64:67], v[146:149], v[212:215], v[64:67]
	v_mfma_f32_16x16x32_bf16 v[60:63], v[154:157], v[212:215], v[60:63]
	v_mfma_f32_16x16x32_bf16 v[48:51], v[146:149], v[220:223], v[48:51]
	v_mfma_f32_16x16x32_bf16 v[44:47], v[154:157], v[220:223], v[44:47]
	v_mfma_f32_16x16x32_bf16 v[32:35], v[146:149], v[228:231], v[32:35]
	v_mfma_f32_16x16x32_bf16 v[28:31], v[154:157], v[228:231], v[28:31]
	v_mfma_f32_16x16x32_bf16 v[16:19], v[146:149], v[236:239], v[16:19]
	v_mfma_f32_16x16x32_bf16 v[12:15], v[154:157], v[236:239], v[12:15]
	v_mfma_f32_16x16x32_bf16 v[56:59], v[158:161], v[208:211], v[56:59]
	v_mfma_f32_16x16x32_bf16 v[52:55], v[180:183], v[208:211], v[52:55]
	v_mfma_f32_16x16x32_bf16 v[40:43], v[158:161], v[216:219], v[40:43]
	v_mfma_f32_16x16x32_bf16 v[36:39], v[180:183], v[216:219], v[36:39]
	v_mfma_f32_16x16x32_bf16 v[24:27], v[158:161], v[224:227], v[24:27]
	v_mfma_f32_16x16x32_bf16 v[20:23], v[180:183], v[224:227], v[20:23]
	v_mfma_f32_16x16x32_bf16 v[8:11], v[158:161], v[232:235], v[8:11]
	v_mfma_f32_16x16x32_bf16 v[4:7], v[180:183], v[232:235], v[4:7]
	v_mfma_f32_16x16x32_bf16 v[56:59], v[174:177], v[212:215], v[56:59]
	v_mfma_f32_16x16x32_bf16 v[52:55], v[204:207], v[212:215], v[52:55]
	v_mfma_f32_16x16x32_bf16 v[40:43], v[174:177], v[220:223], v[40:43]
	v_mfma_f32_16x16x32_bf16 v[36:39], v[204:207], v[220:223], v[36:39]
	v_mfma_f32_16x16x32_bf16 v[24:27], v[174:177], v[228:231], v[24:27]
	v_mfma_f32_16x16x32_bf16 v[20:23], v[204:207], v[228:231], v[20:23]
	v_mfma_f32_16x16x32_bf16 v[8:11], v[174:177], v[236:239], v[8:11]
	v_mfma_f32_16x16x32_bf16 v[4:7], v[204:207], v[236:239], v[4:7]
	s_setprio 3
	s_barrier
; #define PG8_STAGE(bufoff, gbase, voff) do { _Pragma("unroll") for (int _i = 0; _i < 2; ++_i) \
;         __builtin_amdgcn_global_load_lds((const unsigned*)((const char*)(gbase) + (voff)[_i]), (PG8_LAS unsigned*)(lds + (bufoff) + ldsw + _i * 8192), 16, 0, 0); } while (0)
; #define PG8_LDA(dst, b, h) do { _Pragma("unroll") for (int m = 0; m < 4; ++m) _Pragma("unroll") for (int k = 0; k < 2; ++k) dst[m][k] = *(const PG8_LAS bf16x8*)(lds + PG8_SA(b, h) + aoff + m * 2048 + k * 1024); } while (0)
; #define PG8_LDB(dst, b, h) do { _Pragma("unroll") for (int n = 0; n < 2; ++n) _Pragma("unroll") for (int k = 0; k < 2; ++k) dst[n][k] = *(const PG8_LAS bf16x8*)(lds + PG8_SB(b, h) + boff + n * 2048 + k * 1024); } while (0)
; #define PG8_MMA(ai, bj, At, Bt) do { __builtin_amdgcn_s_setprio(1); _Pragma("unroll") for (int m = 0; m < 4; ++m) _Pragma("unroll") for (int n = 0; n < 2; ++n) _Pragma("unroll") for (int k = 0; k < 2; ++k) \
;         acc[ai][bj][m][n] = __builtin_amdgcn_mfma_f32_16x16x32_bf16(Bt[n][k], At[m][k], acc[ai][bj][m][n], 0, 0, 0); __builtin_amdgcn_s_setprio(0); } while (0)
; #define PG8_WAIT_V(n) asm volatile("s_waitcnt vmcnt(" #n ")" ::: "memory")
; #define PG8_WAIT_L(n) asm volatile("s_waitcnt lgkmcnt(" #n ")" ::: "memory")
; #define PG8_BAR __builtin_amdgcn_s_barrier()
; #define PG8_SCHED __builtin_amdgcn_sched_barrier(0)
; template <class Epi, class Sched, bool ALIGN_EPI = false, bool SP2 = false>
; __device__ __forceinline__ void gemm_phase(PG8_LAS unsigned char* lds, const Gemm g, const Sched& S, const Epi& E) {
;     ...
;             PG8_LDB(B0, 1, 0); PG8_LDB(B1, 1, 1); PG8_SCHED; PG8_LDA(At, 1, 0); PG8_STAGE(PG8_SA(0, 1), a2 + hstep, voffA);
;             PG8_WAIT_V(8); PG8_WAIT_L(0); PG8_BAR; PG8_MMA(0, 0, At, B0); PG8_MMA(0, 1, At, B1); PG8_BAR; PG8_SCHED;
;             PG8_LDA(At, 1, 1); PG8_STAGE(PG8_SB(1, 0), b3, voffB); PG8_STAGE(PG8_SB(1, 1), b3 + hstep, voffB); PG8_STAGE(PG8_SA(1, 0), a3, voffA);
;             PG8_WAIT_V(8); PG8_WAIT_L(0); PG8_BAR; PG8_MMA(1, 0, At, B0); PG8_MMA(1, 1, At, B1); PG8_BAR; PG8_SCHED;
	s_add_i32 s37, 0, 0x18000
	s_add_i32 s39, 0, 0x1c000
	ds_read_b128 v[142:145], v243 offset:32768
	ds_read_b128 v[146:149], v243 offset:33792
	ds_read_b128 v[150:153], v243 offset:34816
	ds_read_b128 v[154:157], v243 offset:35840
	ds_read_b128 v[158:161], v243 offset:49152
	ds_read_b128 v[174:177], v243 offset:50176
	ds_read_b128 v[180:183], v243 offset:51200
	ds_read_b128 v[204:207], v243 offset:52224
	s_add_u32 s40, s46, 0x80000
	s_addc_u32 s41, s47, 0
	s_mov_b32 m0, s57
	ds_read_b128 v[208:211], v179 offset:32768
	ds_read_b128 v[212:215], v179 offset:33792
	ds_read_b128 v[216:219], v179 offset:34816
	ds_read_b128 v[220:223], v179 offset:35840
	ds_read_b128 v[224:227], v179 offset:36864
	ds_read_b128 v[228:231], v179 offset:37888
	ds_read_b128 v[232:235], v179 offset:38912
	ds_read_b128 v[236:239], v179 offset:39936
	global_load_lds_dwordx4 v2, s[40:41]
	s_mov_b32 m0, s58
	s_nop 0
	global_load_lds_dwordx4 v132, s[40:41]
	s_nop 0
	s_waitcnt vmcnt(8) lgkmcnt(0)
	s_setprio 0
	s_barrier
	v_mfma_f32_16x16x32_bf16 v[128:131], v[142:145], v[208:211], v[128:131]
	v_mfma_f32_16x16x32_bf16 v[124:127], v[150:153], v[208:211], v[124:127]
	v_mfma_f32_16x16x32_bf16 v[112:115], v[142:145], v[216:219], v[112:115]
	v_mfma_f32_16x16x32_bf16 v[108:111], v[150:153], v[216:219], v[108:111]
	v_mfma_f32_16x16x32_bf16 v[96:99], v[142:145], v[224:227], v[96:99]
	v_mfma_f32_16x16x32_bf16 v[92:95], v[150:153], v[224:227], v[92:95]
	v_mfma_f32_16x16x32_bf16 v[80:83], v[142:145], v[232:235], v[80:83]
	v_mfma_f32_16x16x32_bf16 v[76:79], v[150:153], v[232:235], v[76:79]
	v_mfma_f32_16x16x32_bf16 v[128:131], v[146:149], v[212:215], v[128:131]
	v_mfma_f32_16x16x32_bf16 v[124:127], v[154:157], v[212:215], v[124:127]
	v_mfma_f32_16x16x32_bf16 v[112:115], v[146:149], v[220:223], v[112:115]
	v_mfma_f32_16x16x32_bf16 v[108:111], v[154:157], v[220:223], v[108:111]
	v_mfma_f32_16x16x32_bf16 v[96:99], v[146:149], v[228:231], v[96:99]
	v_mfma_f32_16x16x32_bf16 v[92:95], v[154:157], v[228:231], v[92:95]
	v_mfma_f32_16x16x32_bf16 v[80:83], v[146:149], v[236:239], v[80:83]
	v_mfma_f32_16x16x32_bf16 v[76:79], v[154:157], v[236:239], v[76:79]
	v_mfma_f32_16x16x32_bf16 v[120:123], v[158:161], v[208:211], v[120:123]
	v_mfma_f32_16x16x32_bf16 v[116:119], v[180:183], v[208:211], v[116:119]
	v_mfma_f32_16x16x32_bf16 v[104:107], v[158:161], v[216:219], v[104:107]
	v_mfma_f32_16x16x32_bf16 v[100:103], v[180:183], v[216:219], v[100:103]
	v_mfma_f32_16x16x32_bf16 v[88:91], v[158:161], v[224:227], v[88:91]
	v_mfma_f32_16x16x32_bf16 v[84:87], v[180:183], v[224:227], v[84:87]
	v_mfma_f32_16x16x32_bf16 v[72:75], v[158:161], v[232:235], v[72:75]
	v_mfma_f32_16x16x32_bf16 v[68:71], v[180:183], v[232:235], v[68:71]
	v_mfma_f32_16x16x32_bf16 v[120:123], v[174:177], v[212:215], v[120:123]
	v_mfma_f32_16x16x32_bf16 v[116:119], v[204:207], v[212:215], v[116:119]
	v_mfma_f32_16x16x32_bf16 v[104:107], v[174:177], v[220:223], v[104:107]
	v_mfma_f32_16x16x32_bf16 v[100:103], v[204:207], v[220:223], v[100:103]
	v_mfma_f32_16x16x32_bf16 v[88:91], v[174:177], v[228:231], v[88:91]
	v_mfma_f32_16x16x32_bf16 v[84:87], v[204:207], v[228:231], v[84:87]
	v_mfma_f32_16x16x32_bf16 v[72:75], v[174:177], v[236:239], v[72:75]
	v_mfma_f32_16x16x32_bf16 v[68:71], v[204:207], v[236:239], v[68:71]
	s_setprio 3
	s_barrier
	s_add_i32 s37, s37, s54
	s_add_i32 m0, s37, 0xffffff80
	ds_read_b128 v[208:211], v179 offset:49152
	ds_read_b128 v[212:215], v179 offset:50176
	ds_read_b128 v[216:219], v179 offset:51200
	ds_read_b128 v[220:223], v179 offset:52224
	ds_read_b128 v[224:227], v179 offset:53248
	ds_read_b128 v[228:231], v179 offset:54272
	ds_read_b128 v[232:235], v179 offset:55296
	ds_read_b128 v[236:239], v179 offset:56320
	global_load_lds_dwordx4 v2, s[44:45] offset:128
	s_add_i32 m0, s37, 0x1f80
	s_add_u32 s40, s44, 0x80080
	s_addc_u32 s41, s45, 0
	s_add_i32 s37, s39, s54
	global_load_lds_dwordx4 v132, s[44:45] offset:128
	s_mov_b32 m0, s37
	s_nop 0
	global_load_lds_dwordx4 v2, s[40:41]
	s_add_i32 m0, s37, 0x2000
	s_nop 0
	global_load_lds_dwordx4 v132, s[40:41]
	s_add_i32 m0, s60, 0xffffff80
	s_nop 0
	global_load_lds_dwordx4 v2, s[46:47] offset:128
	s_add_i32 m0, s61, 0xffffff80
	s_nop 0
	global_load_lds_dwordx4 v132, s[46:47] offset:128
	s_nop 0
	s_waitcnt vmcnt(8) lgkmcnt(0)
	s_setprio 0
	s_barrier
	v_mfma_f32_16x16x32_bf16 v[64:67], v[142:145], v[208:211], v[64:67]
	v_mfma_f32_16x16x32_bf16 v[60:63], v[150:153], v[208:211], v[60:63]
	v_mfma_f32_16x16x32_bf16 v[48:51], v[142:145], v[216:219], v[48:51]
	v_mfma_f32_16x16x32_bf16 v[44:47], v[150:153], v[216:219], v[44:47]
	v_mfma_f32_16x16x32_bf16 v[32:35], v[142:145], v[224:227], v[32:35]
	v_mfma_f32_16x16x32_bf16 v[28:31], v[150:153], v[224:227], v[28:31]
	v_mfma_f32_16x16x32_bf16 v[16:19], v[142:145], v[232:235], v[16:19]
	v_mfma_f32_16x16x32_bf16 v[12:15], v[150:153], v[232:235], v[12:15]
	v_mfma_f32_16x16x32_bf16 v[64:67], v[146:149], v[212:215], v[64:67]
	v_mfma_f32_16x16x32_bf16 v[60:63], v[154:157], v[212:215], v[60:63]
	v_mfma_f32_16x16x32_bf16 v[48:51], v[146:149], v[220:223], v[48:51]
	v_mfma_f32_16x16x32_bf16 v[44:47], v[154:157], v[220:223], v[44:47]
	v_mfma_f32_16x16x32_bf16 v[32:35], v[146:149], v[228:231], v[32:35]
	v_mfma_f32_16x16x32_bf16 v[28:31], v[154:157], v[228:231], v[28:31]
	v_mfma_f32_16x16x32_bf16 v[16:19], v[146:149], v[236:239], v[16:19]
	v_mfma_f32_16x16x32_bf16 v[12:15], v[154:157], v[236:239], v[12:15]
	v_mfma_f32_16x16x32_bf16 v[56:59], v[158:161], v[208:211], v[56:59]
	v_mfma_f32_16x16x32_bf16 v[52:55], v[180:183], v[208:211], v[52:55]
	v_mfma_f32_16x16x32_bf16 v[40:43], v[158:161], v[216:219], v[40:43]
	v_mfma_f32_16x16x32_bf16 v[36:39], v[180:183], v[216:219], v[36:39]
	v_mfma_f32_16x16x32_bf16 v[24:27], v[158:161], v[224:227], v[24:27]
	v_mfma_f32_16x16x32_bf16 v[20:23], v[180:183], v[224:227], v[20:23]
	v_mfma_f32_16x16x32_bf16 v[8:11], v[158:161], v[232:235], v[8:11]
	v_mfma_f32_16x16x32_bf16 v[4:7], v[180:183], v[232:235], v[4:7]
	v_mfma_f32_16x16x32_bf16 v[56:59], v[174:177], v[212:215], v[56:59]
	v_mfma_f32_16x16x32_bf16 v[52:55], v[204:207], v[212:215], v[52:55]
	v_mfma_f32_16x16x32_bf16 v[40:43], v[174:177], v[220:223], v[40:43]
	v_mfma_f32_16x16x32_bf16 v[36:39], v[204:207], v[220:223], v[36:39]
	v_mfma_f32_16x16x32_bf16 v[24:27], v[174:177], v[228:231], v[24:27]
	v_mfma_f32_16x16x32_bf16 v[20:23], v[204:207], v[228:231], v[20:23]
	v_mfma_f32_16x16x32_bf16 v[8:11], v[174:177], v[236:239], v[8:11]
	v_mfma_f32_16x16x32_bf16 v[4:7], v[204:207], v[236:239], v[4:7]
	s_setprio 3
	s_barrier
	s_add_i32 s31, s31, 2
	s_add_u32 s2, s2, 0x100
	s_addc_u32 s29, s29, 0
	s_cmp_gt_u32 s31, 29
	s_mov_b64 s[40:41], s[42:43]
	s_cbranch_scc0 .LBB0_2185
	s_and_b64 vcc, exec, s[26:27]
	s_cbranch_vccz .LBB0_2188
	s_barrier
